# in-proj epilogue: lean path for V and gate column groups (one LDS round trip per slab, lane = 4 consecutive columns, SiLU in place, 8-byte row-segment stores)
# speedup vs baseline: 1.0324x; 1.0176x over previous
.LBB0_219:
	s_lshr_b32 s2, s4, 2
	s_and_b32 s3, s4, 3
	s_lshl_b32 s3, s3, 3
	s_mov_b32 s6, 0x1001000a
	s_cmp_eq_u32 s2, 1
	s_cselect_b32 s6, 0x171b0611, s6
	s_cmp_eq_u32 s2, 2
	s_cselect_b32 s6, 0xe1c1d08, s6
	s_cmp_eq_u32 s2, 3
	s_cselect_b32 s6, 0x14090203, s6
	s_cmp_eq_u32 s2, 4
	s_cselect_b32 s6, 0x40f0512, s6
	s_cmp_eq_u32 s2, 5
	s_cselect_b32 s6, 0xc160b0d, s6
	s_cmp_eq_u32 s2, 6
	s_cselect_b32 s6, 0x191a1813, s6
	s_cmp_eq_u32 s2, 7
	s_cselect_b32 s6, 0x1507, s6
	s_lshr_b32 s6, s6, s3
	s_and_b32 s4, s6, 0xff
	s_lshl_b32 s5, s5, 8
	s_mov_b32 s32, s5
	v_add_u32_e32 v2, s5, v219
	v_ashrrev_i32_e32 v3, 31, v2
	v_lshlrev_b64 v[4:5], 11, v[2:3]
	v_and_b32_e32 v6, 0xfffe7000, v4
	v_mov_b32_e32 v7, v5
	v_lshlrev_b32_e32 v0, 6, v2
	s_lshl_b32 s6, s4, 7
	v_lshl_add_u64 v[6:7], s[44:45], 0, v[6:7]
	v_and_b32_e32 v0, 64, v0
	v_lshl_add_u64 v[2:3], v[6:7], 0, v[0:1]
	v_add_u32_e32 v6, s6, v220
	v_ashrrev_i32_e32 v7, 31, v6
	v_lshlrev_b64 v[8:9], 11, v[6:7]
	v_and_b32_e32 v10, 0xffff7000, v8
	v_mov_b32_e32 v11, v9
	v_lshlrev_b32_e32 v0, 6, v6
	v_lshl_add_u64 v[10:11], s[42:43], 0, v[10:11]
	v_and_b32_e32 v0, 64, v0
	v_mov_b32_e32 v139, v1
	v_lshl_add_u64 v[6:7], v[10:11], 0, v[0:1]
	v_readfirstlane_b32 s2, v221
	v_add_u32_e32 v0, 0x400, v221
	v_lshl_add_u64 v[2:3], v[2:3], 0, v[138:139]
	s_nop 0
	s_mov_b32 m0, s2
	s_mov_b64 s[8:9], 0x8000
	v_readfirstlane_b32 s2, v0
	global_load_lds_dwordx4 v[2:3], off
	v_lshl_add_u64 v[10:11], v[2:3], 0, s[8:9]
	s_mov_b32 m0, s2
	s_mov_b64 s[2:3], 0x10000
	v_add_u32_e32 v0, 0x800, v221
	global_load_lds_dwordx4 v[10:11], off
	v_lshl_add_u64 v[10:11], v[2:3], 0, s[2:3]
	v_readfirstlane_b32 s2, v0
	s_mov_b32 m0, s2
	s_mov_b64 s[2:3], 0x18000
	v_add_u32_e32 v0, 0xc00, v221
	global_load_lds_dwordx4 v[10:11], off
	v_lshl_add_u64 v[10:11], v[2:3], 0, s[2:3]
	v_readfirstlane_b32 s2, v0
	v_add_u32_e32 v0, 0x4000, v130
	s_mov_b32 m0, s2
	v_readfirstlane_b32 s2, v0
	v_add_u32_e32 v0, 0x4400, v130
	v_lshl_add_u64 v[6:7], v[6:7], 0, v[138:139]
	global_load_lds_dwordx4 v[10:11], off
	s_mov_b32 m0, s2
	v_readfirstlane_b32 s2, v0
	v_add_u32_e32 v0, 0x6000, v221
	global_load_lds_dwordx4 v[6:7], off
	v_lshl_add_u64 v[10:11], v[6:7], 0, s[8:9]
	s_mov_b32 m0, s2
	s_mov_b64 s[8:9], 0x80
	v_readfirstlane_b32 s2, v0
	v_add_u32_e32 v0, 0x6400, v221
	global_load_lds_dwordx4 v[10:11], off
	v_lshl_add_u64 v[10:11], v[2:3], 0, s[8:9]
	s_mov_b32 m0, s2
	s_mov_b64 s[30:31], 0x8080
	v_readfirstlane_b32 s2, v0
	global_load_lds_dwordx4 v[10:11], off
	v_lshl_add_u64 v[10:11], v[2:3], 0, s[30:31]
	s_mov_b32 m0, s2
	s_mov_b64 s[2:3], 0x10080
	v_add_u32_e32 v0, 0x6800, v221
	global_load_lds_dwordx4 v[10:11], off
	v_lshl_add_u64 v[10:11], v[2:3], 0, s[2:3]
	v_readfirstlane_b32 s2, v0
	s_mov_b32 m0, s2
	s_mov_b64 s[2:3], 0x18080
	v_add_u32_e32 v0, 0x6c00, v221
	v_lshl_add_u64 v[2:3], v[2:3], 0, s[2:3]
	v_readfirstlane_b32 s2, v0
	v_add_u32_e32 v0, 0xa000, v130
	global_load_lds_dwordx4 v[10:11], off
	s_mov_b32 m0, s2
	v_readfirstlane_b32 s2, v0
	v_add_u32_e32 v0, 0xa400, v130
	global_load_lds_dwordx4 v[2:3], off
	v_lshl_add_u64 v[2:3], v[6:7], 0, s[8:9]
	s_mov_b32 m0, s2
	v_readfirstlane_b32 s2, v0
	global_load_lds_dwordx4 v[2:3], off
	v_lshl_add_u64 v[2:3], v[6:7], 0, s[30:31]
	s_mov_b32 m0, s2
	v_and_b32_e32 v8, 0xfffff000, v8
	global_load_lds_dwordx4 v[2:3], off
	v_and_b32_e32 v4, 0xfffff000, v4
	v_mov_b32_e32 v2, 0
	v_lshl_add_u64 v[142:143], v[134:135], 0, v[8:9]
	v_lshl_add_u64 v[144:145], v[136:137], 0, v[4:5]
	s_mov_b32 s7, 0
	s_mov_b64 s[2:3], 0
	v_mov_b32_e32 v3, v2
	v_mov_b32_e32 v4, v2
	v_mov_b32_e32 v5, v2
	v_mov_b32_e32 v6, v2
	v_mov_b32_e32 v7, v2
	v_mov_b32_e32 v8, v2
	v_mov_b32_e32 v9, v2
	v_mov_b32_e32 v10, v2
	v_mov_b32_e32 v11, v2
	v_mov_b32_e32 v12, v2
	v_mov_b32_e32 v13, v2
	v_mov_b32_e32 v14, v2
	v_mov_b32_e32 v15, v2
	v_mov_b32_e32 v16, v2
	v_mov_b32_e32 v17, v2
	v_mov_b32_e32 v18, v2
	v_mov_b32_e32 v19, v2
	v_mov_b32_e32 v20, v2
	v_mov_b32_e32 v21, v2
	v_mov_b32_e32 v22, v2
	v_mov_b32_e32 v23, v2
	v_mov_b32_e32 v24, v2
	v_mov_b32_e32 v25, v2
	v_mov_b32_e32 v26, v2
	v_mov_b32_e32 v27, v2
	v_mov_b32_e32 v28, v2
	v_mov_b32_e32 v29, v2
	v_mov_b32_e32 v30, v2
	v_mov_b32_e32 v31, v2
	v_mov_b32_e32 v32, v2
	v_mov_b32_e32 v33, v2
	v_mov_b32_e32 v34, v2
	v_mov_b32_e32 v35, v2
	v_mov_b32_e32 v36, v2
	v_mov_b32_e32 v37, v2
	v_mov_b32_e32 v38, v2
	v_mov_b32_e32 v39, v2
	v_mov_b32_e32 v40, v2
	v_mov_b32_e32 v41, v2
	v_mov_b32_e32 v42, v2
	v_mov_b32_e32 v43, v2
	v_mov_b32_e32 v44, v2
	v_mov_b32_e32 v45, v2
	v_mov_b32_e32 v46, v2
	v_mov_b32_e32 v47, v2
	v_mov_b32_e32 v48, v2
	v_mov_b32_e32 v49, v2
	s_nop 0
	v_mov_b32_e32 v50, v2
	v_mov_b32_e32 v51, v2
	v_mov_b32_e32 v52, v2
	v_mov_b32_e32 v53, v2
	v_mov_b32_e32 v54, v2
	v_mov_b32_e32 v55, v2
	v_mov_b32_e32 v56, v2
	v_mov_b32_e32 v57, v2
	v_mov_b32_e32 v58, v2
	v_mov_b32_e32 v59, v2
	v_mov_b32_e32 v60, v2
	v_mov_b32_e32 v61, v2
	v_mov_b32_e32 v62, v2
	v_mov_b32_e32 v63, v2
	v_mov_b32_e32 v64, v2
	v_mov_b32_e32 v65, v2
	v_mov_b32_e32 v66, v2
	v_mov_b32_e32 v67, v2
	v_mov_b32_e32 v68, v2
	v_mov_b32_e32 v69, v2
	v_mov_b32_e32 v70, v2
	v_mov_b32_e32 v71, v2
	v_mov_b32_e32 v72, v2
	v_mov_b32_e32 v73, v2
	v_mov_b32_e32 v74, v2
	v_mov_b32_e32 v75, v2
	v_mov_b32_e32 v76, v2
	v_mov_b32_e32 v77, v2
	v_mov_b32_e32 v78, v2
	v_mov_b32_e32 v79, v2
	v_mov_b32_e32 v80, v2
	v_mov_b32_e32 v81, v2
	v_mov_b32_e32 v82, v2
	v_mov_b32_e32 v83, v2
	v_mov_b32_e32 v84, v2
	v_mov_b32_e32 v85, v2
	v_mov_b32_e32 v86, v2
	v_mov_b32_e32 v87, v2
	v_mov_b32_e32 v88, v2
	v_mov_b32_e32 v89, v2
	v_mov_b32_e32 v90, v2
	v_mov_b32_e32 v91, v2
	v_mov_b32_e32 v92, v2
	v_mov_b32_e32 v93, v2
	v_mov_b32_e32 v94, v2
	v_mov_b32_e32 v95, v2
	v_mov_b32_e32 v96, v2
	v_mov_b32_e32 v97, v2
	v_mov_b32_e32 v98, v2
	v_mov_b32_e32 v99, v2
	v_mov_b32_e32 v100, v2
	v_mov_b32_e32 v101, v2
	v_mov_b32_e32 v102, v2
	v_mov_b32_e32 v103, v2
	v_mov_b32_e32 v104, v2
	v_mov_b32_e32 v105, v2
	v_mov_b32_e32 v106, v2
	v_mov_b32_e32 v107, v2
	v_mov_b32_e32 v108, v2
	v_mov_b32_e32 v109, v2
	v_mov_b32_e32 v110, v2
	v_mov_b32_e32 v111, v2
	v_mov_b32_e32 v112, v2
	v_mov_b32_e32 v113, v2
	v_mov_b32_e32 v114, v2
	v_mov_b32_e32 v115, v2
	v_mov_b32_e32 v116, v2
	v_mov_b32_e32 v117, v2
	v_mov_b32_e32 v118, v2
	v_mov_b32_e32 v119, v2
	v_mov_b32_e32 v120, v2
	v_mov_b32_e32 v121, v2
	v_mov_b32_e32 v122, v2
	v_mov_b32_e32 v123, v2
	v_mov_b32_e32 v124, v2
	v_mov_b32_e32 v125, v2
	v_mov_b32_e32 v126, v2
	v_mov_b32_e32 v127, v2
	v_mov_b32_e32 v128, v2
	v_mov_b32_e32 v129, v2
.LBB0_220:
	s_cmp_gt_i32 s7, 0
	s_waitcnt vmcnt(6)
	s_cselect_b32 s8, -1, 2
	s_mul_i32 s9, s7, 0x6000
	s_waitcnt lgkmcnt(0)
	s_add_i32 s8, s8, s7
	v_add_u32_e32 v139, s9, v224
	v_add_u32_e32 v0, s9, v223
	s_mulk_i32 s8, 0x6000
	v_add_u32_e32 v154, v139, v228
	s_barrier
	v_lshl_add_u64 v[170:171], v[144:145], 0, s[2:3]
	v_add_u32_e32 v141, s8, v221
	v_lshl_add_u64 v[174:175], v[142:143], 0, s[2:3]
	v_add_u32_e32 v182, s8, v222
	v_add_u32_e32 v166, v0, v228
	ds_read_b128 v[146:149], v166
	ds_read_b128 v[150:153], v154
	ds_read_b128 v[154:157], v154 offset:2048
	v_lshl_add_u64 v[172:173], v[170:171], 0, s[88:89]
	v_lshl_add_u64 v[176:177], v[174:175], 0, s[88:89]
	v_add_u32_e32 v183, 0x4000, v182
	v_lshl_add_u64 v[178:179], v[170:171], 0, s[90:91]
	v_add_u32_e32 v184, 0x400, v141
	v_lshl_add_u64 v[180:181], v[170:171], 0, s[78:79]
	v_add_u32_e32 v185, 0x800, v141
	ds_read_b128 v[158:161], v166 offset:2048
	ds_read_b128 v[162:165], v166 offset:4096
	ds_read_b128 v[166:169], v166 offset:6144
	s_waitcnt lgkmcnt(3)
	s_setprio 1
	v_mfma_f32_32x32x16_bf16 v[114:129], v[146:149], v[150:153], v[114:129]
	v_mfma_f32_32x32x16_bf16 v[98:113], v[146:149], v[154:157], v[98:113]
	v_readfirstlane_b32 s8, v141
	s_mov_b32 m0, s8
	s_nop 0
	global_load_lds_dwordx4 v[172:173], off
	s_waitcnt lgkmcnt(2)
	v_mfma_f32_32x32x16_bf16 v[82:97], v[158:161], v[150:153], v[82:97]
	v_mfma_f32_32x32x16_bf16 v[66:81], v[158:161], v[154:157], v[66:81]
	v_readfirstlane_b32 s8, v184
	s_mov_b32 m0, s8
	s_nop 0
	global_load_lds_dwordx4 v[178:179], off
	s_waitcnt lgkmcnt(1)
	v_mfma_f32_32x32x16_bf16 v[50:65], v[162:165], v[150:153], v[50:65]
	v_mfma_f32_32x32x16_bf16 v[34:49], v[162:165], v[154:157], v[34:49]
	v_readfirstlane_b32 s8, v185
	s_mov_b32 m0, s8
	s_nop 0
	global_load_lds_dwordx4 v[180:181], off
	s_waitcnt lgkmcnt(0)
	v_mfma_f32_32x32x16_bf16 v[18:33], v[166:169], v[150:153], v[18:33]
	v_mfma_f32_32x32x16_bf16 v[2:17], v[166:169], v[154:157], v[2:17]
	s_setprio 0
	v_add_u32_e32 v0, v0, v229
	v_add_u32_e32 v139, v139, v229
	ds_read_b128 v[146:149], v0
	ds_read_b128 v[150:153], v139
	ds_read_b128 v[154:157], v139 offset:2048
	ds_read_b128 v[158:161], v0 offset:2048
	ds_read_b128 v[162:165], v0 offset:4096
	ds_read_b128 v[166:169], v0 offset:6144
	s_waitcnt lgkmcnt(3)
	s_setprio 1
	v_mfma_f32_32x32x16_bf16 v[114:129], v[146:149], v[150:153], v[114:129]
	v_mfma_f32_32x32x16_bf16 v[98:113], v[146:149], v[154:157], v[98:113]
	v_add_u32_e32 v0, 0xc00, v141
	v_lshl_add_u64 v[146:147], v[170:171], 0, s[76:77]
	v_readfirstlane_b32 s8, v0
	s_mov_b32 m0, s8
	s_nop 0
	global_load_lds_dwordx4 v[146:147], off
	s_waitcnt lgkmcnt(2)
	v_mfma_f32_32x32x16_bf16 v[82:97], v[158:161], v[150:153], v[82:97]
	v_mfma_f32_32x32x16_bf16 v[66:81], v[158:161], v[154:157], v[66:81]
	v_readfirstlane_b32 s8, v183
	s_mov_b32 m0, s8
	s_nop 0
	global_load_lds_dwordx4 v[176:177], off
	s_waitcnt lgkmcnt(1)
	v_mfma_f32_32x32x16_bf16 v[50:65], v[162:165], v[150:153], v[50:65]
	v_mfma_f32_32x32x16_bf16 v[34:49], v[162:165], v[154:157], v[34:49]
	v_add_u32_e32 v0, 0x4400, v182
	v_lshl_add_u64 v[146:147], v[174:175], 0, s[90:91]
	v_readfirstlane_b32 s8, v0
	s_mov_b32 m0, s8
	s_nop 0
	global_load_lds_dwordx4 v[146:147], off
	s_waitcnt lgkmcnt(0)
	v_mfma_f32_32x32x16_bf16 v[18:33], v[166:169], v[150:153], v[18:33]
	v_mfma_f32_32x32x16_bf16 v[2:17], v[166:169], v[154:157], v[2:17]
	s_setprio 0
	s_add_i32 s8, s7, 1
	s_cmp_lt_i32 s7, 2
	s_cselect_b32 s7, s8, 0
	s_add_u32 s2, s2, 0x80
	s_addc_u32 s3, s3, 0
	s_cmpk_eq_i32 s2, 0xf00
	s_cbranch_scc0 .LBB0_220
	s_waitcnt vmcnt(6)
	s_mul_i32 s2, s7, 0x6000
	s_waitcnt lgkmcnt(0)
	v_add_u32_e32 v139, s2, v224
	v_add_u32_e32 v0, s2, v223
	v_add_u32_e32 v150, v139, v228
	s_barrier
	v_add_u32_e32 v141, v0, v228
	ds_read_b128 v[142:145], v141
	ds_read_b128 v[146:149], v150
	ds_read_b128 v[150:153], v150 offset:2048
	ds_read_b128 v[154:157], v141 offset:2048
	ds_read_b128 v[158:161], v141 offset:4096
	ds_read_b128 v[162:165], v141 offset:6144
	s_waitcnt lgkmcnt(3)
	s_setprio 1
	v_mfma_f32_32x32x16_bf16 v[114:129], v[142:145], v[146:149], v[114:129]
	v_mfma_f32_32x32x16_bf16 v[98:113], v[142:145], v[150:153], v[98:113]
	s_waitcnt lgkmcnt(2)
	v_mfma_f32_32x32x16_bf16 v[82:97], v[154:157], v[146:149], v[82:97]
	v_mfma_f32_32x32x16_bf16 v[66:81], v[154:157], v[150:153], v[66:81]
	s_waitcnt lgkmcnt(1)
	v_mfma_f32_32x32x16_bf16 v[50:65], v[158:161], v[146:149], v[50:65]
	v_mfma_f32_32x32x16_bf16 v[34:49], v[158:161], v[150:153], v[34:49]
	s_waitcnt lgkmcnt(0)
	v_mfma_f32_32x32x16_bf16 v[18:33], v[162:165], v[146:149], v[18:33]
	v_mfma_f32_32x32x16_bf16 v[2:17], v[162:165], v[150:153], v[2:17]
	s_setprio 0
	v_add_u32_e32 v0, v0, v229
	v_add_u32_e32 v139, v139, v229
	ds_read_b128 v[142:145], v0
	ds_read_b128 v[146:149], v139
	ds_read_b128 v[150:153], v139 offset:2048
	ds_read_b128 v[154:157], v0 offset:2048
	ds_read_b128 v[158:161], v0 offset:4096
	ds_read_b128 v[162:165], v0 offset:6144
	s_waitcnt lgkmcnt(3)
	s_setprio 1
	v_mfma_f32_32x32x16_bf16 v[114:129], v[142:145], v[146:149], v[114:129]
	v_mfma_f32_32x32x16_bf16 v[98:113], v[142:145], v[150:153], v[98:113]
	s_waitcnt lgkmcnt(2)
	v_mfma_f32_32x32x16_bf16 v[82:97], v[154:157], v[146:149], v[82:97]
	v_mfma_f32_32x32x16_bf16 v[66:81], v[154:157], v[150:153], v[66:81]
	s_waitcnt lgkmcnt(1)
	v_mfma_f32_32x32x16_bf16 v[50:65], v[158:161], v[146:149], v[50:65]
	v_mfma_f32_32x32x16_bf16 v[34:49], v[158:161], v[150:153], v[34:49]
	s_waitcnt lgkmcnt(0)
	v_mfma_f32_32x32x16_bf16 v[18:33], v[162:165], v[146:149], v[18:33]
	v_mfma_f32_32x32x16_bf16 v[2:17], v[162:165], v[150:153], v[2:17]
	s_setprio 0
	s_waitcnt vmcnt(0)
	s_waitcnt lgkmcnt(0)
	s_barrier
	ds_read_b128 v[142:145], v232
	ds_read_b128 v[146:149], v233
	ds_read_b128 v[150:153], v233 offset:2048
	ds_read_b128 v[154:157], v232 offset:2048
	ds_read_b128 v[158:161], v232 offset:4096
	ds_read_b128 v[162:165], v232 offset:6144
	s_waitcnt lgkmcnt(3)
	s_setprio 1
	v_mfma_f32_32x32x16_bf16 v[114:129], v[142:145], v[146:149], v[114:129]
	v_mfma_f32_32x32x16_bf16 v[98:113], v[142:145], v[150:153], v[98:113]
	s_waitcnt lgkmcnt(2)
	v_mfma_f32_32x32x16_bf16 v[82:97], v[154:157], v[146:149], v[82:97]
	v_mfma_f32_32x32x16_bf16 v[66:81], v[154:157], v[150:153], v[66:81]
	s_waitcnt lgkmcnt(1)
	v_mfma_f32_32x32x16_bf16 v[50:65], v[158:161], v[146:149], v[50:65]
	v_mfma_f32_32x32x16_bf16 v[34:49], v[158:161], v[150:153], v[34:49]
	s_waitcnt lgkmcnt(0)
	v_mfma_f32_32x32x16_bf16 v[18:33], v[162:165], v[146:149], v[18:33]
	v_mfma_f32_32x32x16_bf16 v[2:17], v[162:165], v[150:153], v[2:17]
	s_setprio 0
	ds_read_b128 v[142:145], v234
	ds_read_b128 v[146:149], v235
	ds_read_b128 v[150:153], v235 offset:2048
	ds_read_b128 v[154:157], v234 offset:2048
	ds_read_b128 v[158:161], v234 offset:4096
	ds_read_b128 v[162:165], v234 offset:6144
	s_waitcnt lgkmcnt(3)
	s_setprio 1
	v_mfma_f32_32x32x16_bf16 v[114:129], v[142:145], v[146:149], v[114:129]
	v_mfma_f32_32x32x16_bf16 v[98:113], v[142:145], v[150:153], v[98:113]
	s_waitcnt lgkmcnt(2)
	v_mfma_f32_32x32x16_bf16 v[82:97], v[154:157], v[146:149], v[82:97]
	v_mfma_f32_32x32x16_bf16 v[66:81], v[154:157], v[150:153], v[66:81]
	s_waitcnt lgkmcnt(1)
	v_mfma_f32_32x32x16_bf16 v[50:65], v[158:161], v[146:149], v[50:65]
	v_mfma_f32_32x32x16_bf16 v[34:49], v[158:161], v[150:153], v[34:49]
	s_waitcnt lgkmcnt(0)
	v_mfma_f32_32x32x16_bf16 v[18:33], v[162:165], v[146:149], v[18:33]
	v_mfma_f32_32x32x16_bf16 v[2:17], v[162:165], v[150:153], v[2:17]
	s_setprio 0
	s_cmp_gt_i32 s4, 3
	s_cselect_b64 s[30:31], -1, 0
	s_add_i32 s2, s4, -8
	s_cmp_gt_u32 s2, 5
	s_cselect_b64 s[98:99], -1, 0
	s_and_b32 s2, s4, 0x7ffffffc
	s_cmp_lg_u32 s2, 20
	v_add_u32_e32 v238, s5, v225
	s_cselect_b64 s[2:3], -1, 0
	s_and_b32 s5, s4, 0x7ffffffe
	s_cmp_eq_u32 s5, 6
	s_cselect_b64 s[82:83], -1, 0
	s_sub_i32 s5, s4, 17
	v_add_u32_e32 v239, 0x800, v230
	v_add_u32_e32 v240, 0x1000, v230
	v_add_u32_e32 v241, 0x1800, v230
	s_waitcnt vmcnt(0) lgkmcnt(0)
	s_barrier
	s_mov_b32 s8, 0x0701c030
	s_mov_b32 s34, 0x380e00c0
	s_lshr_b32 s8, s8, s4
	s_lshr_b32 s34, s34, s4
	s_and_b32 s8, s8, 1
	s_and_b32 s34, s34, 1
	s_or_b32 s7, s8, s34
	s_cmp_eq_u32 s7, 0
	s_cbranch_scc1 .Lmy_g0e_std
	v_and_b32_e32 v151, 63, v200
	v_lshrrev_b32_e32 v150, 5, v151
	v_and_b32_e32 v146, 31, v151
	v_lshrrev_b32_e32 v147, 6, v200
	v_lshrrev_b32_e32 v152, 1, v147
	v_and_b32_e32 v148, 1, v147
	v_mul_u32_u24_e32 v147, 0x2200, v147
	v_lshlrev_b32_e32 v146, 2, v146
	s_movk_i32 s6, 0x440
	v_mad_u32_u24 v146, v150, s6, v146
	v_add_u32_e32 v146, v146, v147
	v_lshrrev_b32_e32 v150, 4, v151
	v_and_b32_e32 v149, 15, v151
	s_movk_i32 s6, 0x110
	v_mad_u32_u24 v147, v150, s6, v147
	v_lshl_add_u32 v147, v149, 4, v147
	v_lshl_add_u32 v152, v152, 7, s32
	v_add_u32_e32 v152, v152, v150
	s_lshl_b32 s6, s4, 7
	v_lshl_add_u32 v148, v148, 6, s6
	v_lshl_add_u32 v148, v149, 2, v148
	v_lshlrev_b32_e32 v148, 1, v148
	v_mul_u32_u24_e32 v152, 0x1e00, v152
	v_add_u32_e32 v148, v148, v152
	s_mov_b64 s[8:9], s[64:65]
	s_cmp_eq_u32 s34, 1
	s_cbranch_scc1 .Lmy_g0e_gate
	ds_write2_b32 v146, v114, v98 offset0:0 offset1:32
	ds_write2_b32 v146, v115, v99 offset0:68 offset1:100
	ds_write2_b32 v146, v116, v100 offset0:136 offset1:168
	ds_write2_b32 v146, v117, v101 offset0:204 offset1:236
	v_add_u32_e32 v146, 0x880, v146
	ds_write2_b32 v146, v118, v102 offset0:0 offset1:32
	ds_write2_b32 v146, v119, v103 offset0:68 offset1:100
	ds_write2_b32 v146, v120, v104 offset0:136 offset1:168
	ds_write2_b32 v146, v121, v105 offset0:204 offset1:236
	v_add_u32_e32 v146, 0x880, v146
	ds_write2_b32 v146, v122, v106 offset0:0 offset1:32
	ds_write2_b32 v146, v123, v107 offset0:68 offset1:100
	ds_write2_b32 v146, v124, v108 offset0:136 offset1:168
	ds_write2_b32 v146, v125, v109 offset0:204 offset1:236
	v_add_u32_e32 v146, 0x880, v146
	ds_write2_b32 v146, v126, v110 offset0:0 offset1:32
	ds_write2_b32 v146, v127, v111 offset0:68 offset1:100
	ds_write2_b32 v146, v128, v112 offset0:136 offset1:168
	ds_write2_b32 v146, v129, v113 offset0:204 offset1:236
	v_subrev_u32_e32 v146, 0x1980, v146
	s_waitcnt lgkmcnt(0)
	ds_read_b128 v[98:101], v147
	ds_read_b128 v[102:105], v147 offset:1088
	ds_read_b128 v[106:109], v147 offset:2176
	ds_read_b128 v[110:113], v147 offset:3264
	ds_read_b128 v[114:117], v147 offset:4352
	ds_read_b128 v[118:121], v147 offset:5440
	ds_read_b128 v[122:125], v147 offset:6528
	ds_read_b128 v[126:129], v147 offset:7616
	s_waitcnt lgkmcnt(7)
	v_cvt_pk_bf16_f32 v154, v98, v99
	v_cvt_pk_bf16_f32 v155, v100, v101
	global_store_dwordx2 v148, v[154:155], s[8:9]
	s_add_u32 s8, s8, 0x7800
	s_addc_u32 s9, s9, 0
	s_waitcnt lgkmcnt(6)
	v_cvt_pk_bf16_f32 v156, v102, v103
	v_cvt_pk_bf16_f32 v157, v104, v105
	global_store_dwordx2 v148, v[156:157], s[8:9]
	s_add_u32 s8, s8, 0x7800
	s_addc_u32 s9, s9, 0
	s_waitcnt lgkmcnt(5)
	v_cvt_pk_bf16_f32 v158, v106, v107
	v_cvt_pk_bf16_f32 v159, v108, v109
	global_store_dwordx2 v148, v[158:159], s[8:9]
	s_add_u32 s8, s8, 0x7800
	s_addc_u32 s9, s9, 0
	s_waitcnt lgkmcnt(4)
	v_cvt_pk_bf16_f32 v160, v110, v111
	v_cvt_pk_bf16_f32 v161, v112, v113
	global_store_dwordx2 v148, v[160:161], s[8:9]
	s_add_u32 s8, s8, 0x7800
	s_addc_u32 s9, s9, 0
	s_waitcnt lgkmcnt(3)
	v_cvt_pk_bf16_f32 v162, v114, v115
	v_cvt_pk_bf16_f32 v163, v116, v117
	global_store_dwordx2 v148, v[162:163], s[8:9]
	s_add_u32 s8, s8, 0x7800
	s_addc_u32 s9, s9, 0
	s_waitcnt lgkmcnt(2)
	v_cvt_pk_bf16_f32 v164, v118, v119
	v_cvt_pk_bf16_f32 v165, v120, v121
	global_store_dwordx2 v148, v[164:165], s[8:9]
	s_add_u32 s8, s8, 0x7800
	s_addc_u32 s9, s9, 0
	s_waitcnt lgkmcnt(1)
	v_cvt_pk_bf16_f32 v166, v122, v123
	v_cvt_pk_bf16_f32 v167, v124, v125
	global_store_dwordx2 v148, v[166:167], s[8:9]
	s_add_u32 s8, s8, 0x7800
	s_addc_u32 s9, s9, 0
	s_waitcnt lgkmcnt(0)
	v_cvt_pk_bf16_f32 v168, v126, v127
	v_cvt_pk_bf16_f32 v169, v128, v129
	global_store_dwordx2 v148, v[168:169], s[8:9]
	s_add_u32 s8, s8, 0x7800
	s_addc_u32 s9, s9, 0
	ds_write2_b32 v146, v82, v66 offset0:0 offset1:32
	ds_write2_b32 v146, v83, v67 offset0:68 offset1:100
	ds_write2_b32 v146, v84, v68 offset0:136 offset1:168
	ds_write2_b32 v146, v85, v69 offset0:204 offset1:236
	v_add_u32_e32 v146, 0x880, v146
	ds_write2_b32 v146, v86, v70 offset0:0 offset1:32
	ds_write2_b32 v146, v87, v71 offset0:68 offset1:100
	ds_write2_b32 v146, v88, v72 offset0:136 offset1:168
	ds_write2_b32 v146, v89, v73 offset0:204 offset1:236
	v_add_u32_e32 v146, 0x880, v146
	ds_write2_b32 v146, v90, v74 offset0:0 offset1:32
	ds_write2_b32 v146, v91, v75 offset0:68 offset1:100
	ds_write2_b32 v146, v92, v76 offset0:136 offset1:168
	ds_write2_b32 v146, v93, v77 offset0:204 offset1:236
	v_add_u32_e32 v146, 0x880, v146
	ds_write2_b32 v146, v94, v78 offset0:0 offset1:32
	ds_write2_b32 v146, v95, v79 offset0:68 offset1:100
	ds_write2_b32 v146, v96, v80 offset0:136 offset1:168
	ds_write2_b32 v146, v97, v81 offset0:204 offset1:236
	v_subrev_u32_e32 v146, 0x1980, v146
	s_waitcnt lgkmcnt(0)
	ds_read_b128 v[66:69], v147
	ds_read_b128 v[70:73], v147 offset:1088
	ds_read_b128 v[74:77], v147 offset:2176
	ds_read_b128 v[78:81], v147 offset:3264
	ds_read_b128 v[82:85], v147 offset:4352
	ds_read_b128 v[86:89], v147 offset:5440
	ds_read_b128 v[90:93], v147 offset:6528
	ds_read_b128 v[94:97], v147 offset:7616
	s_waitcnt lgkmcnt(7)
	v_cvt_pk_bf16_f32 v154, v66, v67
	v_cvt_pk_bf16_f32 v155, v68, v69
	global_store_dwordx2 v148, v[154:155], s[8:9]
	s_add_u32 s8, s8, 0x7800
	s_addc_u32 s9, s9, 0
	s_waitcnt lgkmcnt(6)
	v_cvt_pk_bf16_f32 v156, v70, v71
	v_cvt_pk_bf16_f32 v157, v72, v73
	global_store_dwordx2 v148, v[156:157], s[8:9]
	s_add_u32 s8, s8, 0x7800
	s_addc_u32 s9, s9, 0
	s_waitcnt lgkmcnt(5)
	v_cvt_pk_bf16_f32 v158, v74, v75
	v_cvt_pk_bf16_f32 v159, v76, v77
	global_store_dwordx2 v148, v[158:159], s[8:9]
	s_add_u32 s8, s8, 0x7800
	s_addc_u32 s9, s9, 0
	s_waitcnt lgkmcnt(4)
	v_cvt_pk_bf16_f32 v160, v78, v79
	v_cvt_pk_bf16_f32 v161, v80, v81
	global_store_dwordx2 v148, v[160:161], s[8:9]
	s_add_u32 s8, s8, 0x7800
	s_addc_u32 s9, s9, 0
	s_waitcnt lgkmcnt(3)
	v_cvt_pk_bf16_f32 v162, v82, v83
	v_cvt_pk_bf16_f32 v163, v84, v85
	global_store_dwordx2 v148, v[162:163], s[8:9]
	s_add_u32 s8, s8, 0x7800
	s_addc_u32 s9, s9, 0
	s_waitcnt lgkmcnt(2)
	v_cvt_pk_bf16_f32 v164, v86, v87
	v_cvt_pk_bf16_f32 v165, v88, v89
	global_store_dwordx2 v148, v[164:165], s[8:9]
	s_add_u32 s8, s8, 0x7800
	s_addc_u32 s9, s9, 0
	s_waitcnt lgkmcnt(1)
	v_cvt_pk_bf16_f32 v166, v90, v91
	v_cvt_pk_bf16_f32 v167, v92, v93
	global_store_dwordx2 v148, v[166:167], s[8:9]
	s_add_u32 s8, s8, 0x7800
	s_addc_u32 s9, s9, 0
	s_waitcnt lgkmcnt(0)
	v_cvt_pk_bf16_f32 v168, v94, v95
	v_cvt_pk_bf16_f32 v169, v96, v97
	global_store_dwordx2 v148, v[168:169], s[8:9]
	s_add_u32 s8, s8, 0x7800
	s_addc_u32 s9, s9, 0
	ds_write2_b32 v146, v50, v34 offset0:0 offset1:32
	ds_write2_b32 v146, v51, v35 offset0:68 offset1:100
	ds_write2_b32 v146, v52, v36 offset0:136 offset1:168
	ds_write2_b32 v146, v53, v37 offset0:204 offset1:236
	v_add_u32_e32 v146, 0x880, v146
	ds_write2_b32 v146, v54, v38 offset0:0 offset1:32
	ds_write2_b32 v146, v55, v39 offset0:68 offset1:100
	ds_write2_b32 v146, v56, v40 offset0:136 offset1:168
	ds_write2_b32 v146, v57, v41 offset0:204 offset1:236
	v_add_u32_e32 v146, 0x880, v146
	ds_write2_b32 v146, v58, v42 offset0:0 offset1:32
	ds_write2_b32 v146, v59, v43 offset0:68 offset1:100
	ds_write2_b32 v146, v60, v44 offset0:136 offset1:168
	ds_write2_b32 v146, v61, v45 offset0:204 offset1:236
	v_add_u32_e32 v146, 0x880, v146
	ds_write2_b32 v146, v62, v46 offset0:0 offset1:32
	ds_write2_b32 v146, v63, v47 offset0:68 offset1:100
	ds_write2_b32 v146, v64, v48 offset0:136 offset1:168
	ds_write2_b32 v146, v65, v49 offset0:204 offset1:236
	v_subrev_u32_e32 v146, 0x1980, v146
	s_waitcnt lgkmcnt(0)
	ds_read_b128 v[34:37], v147
	ds_read_b128 v[38:41], v147 offset:1088
	ds_read_b128 v[42:45], v147 offset:2176
	ds_read_b128 v[46:49], v147 offset:3264
	ds_read_b128 v[50:53], v147 offset:4352
	ds_read_b128 v[54:57], v147 offset:5440
	ds_read_b128 v[58:61], v147 offset:6528
	ds_read_b128 v[62:65], v147 offset:7616
	s_waitcnt lgkmcnt(7)
	v_cvt_pk_bf16_f32 v154, v34, v35
	v_cvt_pk_bf16_f32 v155, v36, v37
	global_store_dwordx2 v148, v[154:155], s[8:9]
	s_add_u32 s8, s8, 0x7800
	s_addc_u32 s9, s9, 0
	s_waitcnt lgkmcnt(6)
	v_cvt_pk_bf16_f32 v156, v38, v39
	v_cvt_pk_bf16_f32 v157, v40, v41
	global_store_dwordx2 v148, v[156:157], s[8:9]
	s_add_u32 s8, s8, 0x7800
	s_addc_u32 s9, s9, 0
	s_waitcnt lgkmcnt(5)
	v_cvt_pk_bf16_f32 v158, v42, v43
	v_cvt_pk_bf16_f32 v159, v44, v45
	global_store_dwordx2 v148, v[158:159], s[8:9]
	s_add_u32 s8, s8, 0x7800
	s_addc_u32 s9, s9, 0
	s_waitcnt lgkmcnt(4)
	v_cvt_pk_bf16_f32 v160, v46, v47
	v_cvt_pk_bf16_f32 v161, v48, v49
	global_store_dwordx2 v148, v[160:161], s[8:9]
	s_add_u32 s8, s8, 0x7800
	s_addc_u32 s9, s9, 0
	s_waitcnt lgkmcnt(3)
	v_cvt_pk_bf16_f32 v162, v50, v51
	v_cvt_pk_bf16_f32 v163, v52, v53
	global_store_dwordx2 v148, v[162:163], s[8:9]
	s_add_u32 s8, s8, 0x7800
	s_addc_u32 s9, s9, 0
	s_waitcnt lgkmcnt(2)
	v_cvt_pk_bf16_f32 v164, v54, v55
	v_cvt_pk_bf16_f32 v165, v56, v57
	global_store_dwordx2 v148, v[164:165], s[8:9]
	s_add_u32 s8, s8, 0x7800
	s_addc_u32 s9, s9, 0
	s_waitcnt lgkmcnt(1)
	v_cvt_pk_bf16_f32 v166, v58, v59
	v_cvt_pk_bf16_f32 v167, v60, v61
	global_store_dwordx2 v148, v[166:167], s[8:9]
	s_add_u32 s8, s8, 0x7800
	s_addc_u32 s9, s9, 0
	s_waitcnt lgkmcnt(0)
	v_cvt_pk_bf16_f32 v168, v62, v63
	v_cvt_pk_bf16_f32 v169, v64, v65
	global_store_dwordx2 v148, v[168:169], s[8:9]
	s_add_u32 s8, s8, 0x7800
	s_addc_u32 s9, s9, 0
	ds_write2_b32 v146, v18, v2 offset0:0 offset1:32
	ds_write2_b32 v146, v19, v3 offset0:68 offset1:100
	ds_write2_b32 v146, v20, v4 offset0:136 offset1:168
	ds_write2_b32 v146, v21, v5 offset0:204 offset1:236
	v_add_u32_e32 v146, 0x880, v146
	ds_write2_b32 v146, v22, v6 offset0:0 offset1:32
	ds_write2_b32 v146, v23, v7 offset0:68 offset1:100
	ds_write2_b32 v146, v24, v8 offset0:136 offset1:168
	ds_write2_b32 v146, v25, v9 offset0:204 offset1:236
	v_add_u32_e32 v146, 0x880, v146
	ds_write2_b32 v146, v26, v10 offset0:0 offset1:32
	ds_write2_b32 v146, v27, v11 offset0:68 offset1:100
	ds_write2_b32 v146, v28, v12 offset0:136 offset1:168
	ds_write2_b32 v146, v29, v13 offset0:204 offset1:236
	v_add_u32_e32 v146, 0x880, v146
	ds_write2_b32 v146, v30, v14 offset0:0 offset1:32
	ds_write2_b32 v146, v31, v15 offset0:68 offset1:100
	ds_write2_b32 v146, v32, v16 offset0:136 offset1:168
	ds_write2_b32 v146, v33, v17 offset0:204 offset1:236
	v_subrev_u32_e32 v146, 0x1980, v146
	s_waitcnt lgkmcnt(0)
	ds_read_b128 v[2:5], v147
	ds_read_b128 v[6:9], v147 offset:1088
	ds_read_b128 v[10:13], v147 offset:2176
	ds_read_b128 v[14:17], v147 offset:3264
	ds_read_b128 v[18:21], v147 offset:4352
	ds_read_b128 v[22:25], v147 offset:5440
	ds_read_b128 v[26:29], v147 offset:6528
	ds_read_b128 v[30:33], v147 offset:7616
	s_waitcnt lgkmcnt(7)
	v_cvt_pk_bf16_f32 v154, v2, v3
	v_cvt_pk_bf16_f32 v155, v4, v5
	global_store_dwordx2 v148, v[154:155], s[8:9]
	s_add_u32 s8, s8, 0x7800
	s_addc_u32 s9, s9, 0
	s_waitcnt lgkmcnt(6)
	v_cvt_pk_bf16_f32 v156, v6, v7
	v_cvt_pk_bf16_f32 v157, v8, v9
	global_store_dwordx2 v148, v[156:157], s[8:9]
	s_add_u32 s8, s8, 0x7800
	s_addc_u32 s9, s9, 0
	s_waitcnt lgkmcnt(5)
	v_cvt_pk_bf16_f32 v158, v10, v11
	v_cvt_pk_bf16_f32 v159, v12, v13
	global_store_dwordx2 v148, v[158:159], s[8:9]
	s_add_u32 s8, s8, 0x7800
	s_addc_u32 s9, s9, 0
	s_waitcnt lgkmcnt(4)
	v_cvt_pk_bf16_f32 v160, v14, v15
	v_cvt_pk_bf16_f32 v161, v16, v17
	global_store_dwordx2 v148, v[160:161], s[8:9]
	s_add_u32 s8, s8, 0x7800
	s_addc_u32 s9, s9, 0
	s_waitcnt lgkmcnt(3)
	v_cvt_pk_bf16_f32 v162, v18, v19
	v_cvt_pk_bf16_f32 v163, v20, v21
	global_store_dwordx2 v148, v[162:163], s[8:9]
	s_add_u32 s8, s8, 0x7800
	s_addc_u32 s9, s9, 0
	s_waitcnt lgkmcnt(2)
	v_cvt_pk_bf16_f32 v164, v22, v23
	v_cvt_pk_bf16_f32 v165, v24, v25
	global_store_dwordx2 v148, v[164:165], s[8:9]
	s_add_u32 s8, s8, 0x7800
	s_addc_u32 s9, s9, 0
	s_waitcnt lgkmcnt(1)
	v_cvt_pk_bf16_f32 v166, v26, v27
	v_cvt_pk_bf16_f32 v167, v28, v29
	global_store_dwordx2 v148, v[166:167], s[8:9]
	s_add_u32 s8, s8, 0x7800
	s_addc_u32 s9, s9, 0
	s_waitcnt lgkmcnt(0)
	v_cvt_pk_bf16_f32 v168, v30, v31
	v_cvt_pk_bf16_f32 v169, v32, v33
	global_store_dwordx2 v148, v[168:169], s[8:9]
	s_add_u32 s8, s8, 0x7800
	s_addc_u32 s9, s9, 0
	s_add_i32 s70, s70, s10
	s_cmp_lt_i32 s70, s71
	s_waitcnt lgkmcnt(0)
	s_barrier
	s_cbranch_scc0 .LBB0_209
	s_branch .LBB0_215
.Lmy_g0e_gate:
	ds_write2_b32 v146, v114, v98 offset0:0 offset1:32
	ds_write2_b32 v146, v115, v99 offset0:68 offset1:100
	ds_write2_b32 v146, v116, v100 offset0:136 offset1:168
	ds_write2_b32 v146, v117, v101 offset0:204 offset1:236
	v_add_u32_e32 v146, 0x880, v146
	ds_write2_b32 v146, v118, v102 offset0:0 offset1:32
	ds_write2_b32 v146, v119, v103 offset0:68 offset1:100
	ds_write2_b32 v146, v120, v104 offset0:136 offset1:168
	ds_write2_b32 v146, v121, v105 offset0:204 offset1:236
	v_add_u32_e32 v146, 0x880, v146
	ds_write2_b32 v146, v122, v106 offset0:0 offset1:32
	ds_write2_b32 v146, v123, v107 offset0:68 offset1:100
	ds_write2_b32 v146, v124, v108 offset0:136 offset1:168
	ds_write2_b32 v146, v125, v109 offset0:204 offset1:236
	v_add_u32_e32 v146, 0x880, v146
	ds_write2_b32 v146, v126, v110 offset0:0 offset1:32
	ds_write2_b32 v146, v127, v111 offset0:68 offset1:100
	ds_write2_b32 v146, v128, v112 offset0:136 offset1:168
	ds_write2_b32 v146, v129, v113 offset0:204 offset1:236
	v_subrev_u32_e32 v146, 0x1980, v146
	s_waitcnt lgkmcnt(0)
	ds_read_b128 v[98:101], v147
	ds_read_b128 v[102:105], v147 offset:1088
	ds_read_b128 v[106:109], v147 offset:2176
	ds_read_b128 v[110:113], v147 offset:3264
	ds_read_b128 v[114:117], v147 offset:4352
	ds_read_b128 v[118:121], v147 offset:5440
	ds_read_b128 v[122:125], v147 offset:6528
	ds_read_b128 v[126:129], v147 offset:7616
	s_waitcnt lgkmcnt(7)
	v_mul_f32_e32 v170, 0xbfb8aa3b, v98
	v_mul_f32_e32 v171, 0xbfb8aa3b, v99
	v_mul_f32_e32 v172, 0xbfb8aa3b, v100
	v_mul_f32_e32 v173, 0xbfb8aa3b, v101
	v_exp_f32_e32 v170, v170
	v_exp_f32_e32 v171, v171
	v_exp_f32_e32 v172, v172
	v_exp_f32_e32 v173, v173
	v_add_f32_e32 v170, 1.0, v170
	v_add_f32_e32 v171, 1.0, v171
	v_add_f32_e32 v172, 1.0, v172
	v_add_f32_e32 v173, 1.0, v173
	v_rcp_f32_e32 v170, v170
	v_rcp_f32_e32 v171, v171
	v_rcp_f32_e32 v172, v172
	v_rcp_f32_e32 v173, v173
	s_nop 0
	v_mul_f32_e32 v98, v98, v170
	v_mul_f32_e32 v99, v99, v171
	v_mul_f32_e32 v100, v100, v172
	v_mul_f32_e32 v101, v101, v173
	v_cvt_pk_bf16_f32 v154, v98, v99
	v_cvt_pk_bf16_f32 v155, v100, v101
	global_store_dwordx2 v148, v[154:155], s[8:9]
	s_add_u32 s8, s8, 0x7800
	s_addc_u32 s9, s9, 0
	s_waitcnt lgkmcnt(6)
	v_mul_f32_e32 v170, 0xbfb8aa3b, v102
	v_mul_f32_e32 v171, 0xbfb8aa3b, v103
	v_mul_f32_e32 v172, 0xbfb8aa3b, v104
	v_mul_f32_e32 v173, 0xbfb8aa3b, v105
	v_exp_f32_e32 v170, v170
	v_exp_f32_e32 v171, v171
	v_exp_f32_e32 v172, v172
	v_exp_f32_e32 v173, v173
	v_add_f32_e32 v170, 1.0, v170
	v_add_f32_e32 v171, 1.0, v171
	v_add_f32_e32 v172, 1.0, v172
	v_add_f32_e32 v173, 1.0, v173
	v_rcp_f32_e32 v170, v170
	v_rcp_f32_e32 v171, v171
	v_rcp_f32_e32 v172, v172
	v_rcp_f32_e32 v173, v173
	s_nop 0
	v_mul_f32_e32 v102, v102, v170
	v_mul_f32_e32 v103, v103, v171
	v_mul_f32_e32 v104, v104, v172
	v_mul_f32_e32 v105, v105, v173
	v_cvt_pk_bf16_f32 v156, v102, v103
	v_cvt_pk_bf16_f32 v157, v104, v105
	global_store_dwordx2 v148, v[156:157], s[8:9]
	s_add_u32 s8, s8, 0x7800
	s_addc_u32 s9, s9, 0
	s_waitcnt lgkmcnt(5)
	v_mul_f32_e32 v170, 0xbfb8aa3b, v106
	v_mul_f32_e32 v171, 0xbfb8aa3b, v107
	v_mul_f32_e32 v172, 0xbfb8aa3b, v108
	v_mul_f32_e32 v173, 0xbfb8aa3b, v109
	v_exp_f32_e32 v170, v170
	v_exp_f32_e32 v171, v171
	v_exp_f32_e32 v172, v172
	v_exp_f32_e32 v173, v173
	v_add_f32_e32 v170, 1.0, v170
	v_add_f32_e32 v171, 1.0, v171
	v_add_f32_e32 v172, 1.0, v172
	v_add_f32_e32 v173, 1.0, v173
	v_rcp_f32_e32 v170, v170
	v_rcp_f32_e32 v171, v171
	v_rcp_f32_e32 v172, v172
	v_rcp_f32_e32 v173, v173
	s_nop 0
	v_mul_f32_e32 v106, v106, v170
	v_mul_f32_e32 v107, v107, v171
	v_mul_f32_e32 v108, v108, v172
	v_mul_f32_e32 v109, v109, v173
	v_cvt_pk_bf16_f32 v158, v106, v107
	v_cvt_pk_bf16_f32 v159, v108, v109
	global_store_dwordx2 v148, v[158:159], s[8:9]
	s_add_u32 s8, s8, 0x7800
	s_addc_u32 s9, s9, 0
	s_waitcnt lgkmcnt(4)
	v_mul_f32_e32 v170, 0xbfb8aa3b, v110
	v_mul_f32_e32 v171, 0xbfb8aa3b, v111
	v_mul_f32_e32 v172, 0xbfb8aa3b, v112
	v_mul_f32_e32 v173, 0xbfb8aa3b, v113
	v_exp_f32_e32 v170, v170
	v_exp_f32_e32 v171, v171
	v_exp_f32_e32 v172, v172
	v_exp_f32_e32 v173, v173
	v_add_f32_e32 v170, 1.0, v170
	v_add_f32_e32 v171, 1.0, v171
	v_add_f32_e32 v172, 1.0, v172
	v_add_f32_e32 v173, 1.0, v173
	v_rcp_f32_e32 v170, v170
	v_rcp_f32_e32 v171, v171
	v_rcp_f32_e32 v172, v172
	v_rcp_f32_e32 v173, v173
	s_nop 0
	v_mul_f32_e32 v110, v110, v170
	v_mul_f32_e32 v111, v111, v171
	v_mul_f32_e32 v112, v112, v172
	v_mul_f32_e32 v113, v113, v173
	v_cvt_pk_bf16_f32 v160, v110, v111
	v_cvt_pk_bf16_f32 v161, v112, v113
	global_store_dwordx2 v148, v[160:161], s[8:9]
	s_add_u32 s8, s8, 0x7800
	s_addc_u32 s9, s9, 0
	s_waitcnt lgkmcnt(3)
	v_mul_f32_e32 v170, 0xbfb8aa3b, v114
	v_mul_f32_e32 v171, 0xbfb8aa3b, v115
	v_mul_f32_e32 v172, 0xbfb8aa3b, v116
	v_mul_f32_e32 v173, 0xbfb8aa3b, v117
	v_exp_f32_e32 v170, v170
	v_exp_f32_e32 v171, v171
	v_exp_f32_e32 v172, v172
	v_exp_f32_e32 v173, v173
	v_add_f32_e32 v170, 1.0, v170
	v_add_f32_e32 v171, 1.0, v171
	v_add_f32_e32 v172, 1.0, v172
	v_add_f32_e32 v173, 1.0, v173
	v_rcp_f32_e32 v170, v170
	v_rcp_f32_e32 v171, v171
	v_rcp_f32_e32 v172, v172
	v_rcp_f32_e32 v173, v173
	s_nop 0
	v_mul_f32_e32 v114, v114, v170
	v_mul_f32_e32 v115, v115, v171
	v_mul_f32_e32 v116, v116, v172
	v_mul_f32_e32 v117, v117, v173
	v_cvt_pk_bf16_f32 v162, v114, v115
	v_cvt_pk_bf16_f32 v163, v116, v117
	global_store_dwordx2 v148, v[162:163], s[8:9]
	s_add_u32 s8, s8, 0x7800
	s_addc_u32 s9, s9, 0
	s_waitcnt lgkmcnt(2)
	v_mul_f32_e32 v170, 0xbfb8aa3b, v118
	v_mul_f32_e32 v171, 0xbfb8aa3b, v119
	v_mul_f32_e32 v172, 0xbfb8aa3b, v120
	v_mul_f32_e32 v173, 0xbfb8aa3b, v121
	v_exp_f32_e32 v170, v170
	v_exp_f32_e32 v171, v171
	v_exp_f32_e32 v172, v172
	v_exp_f32_e32 v173, v173
	v_add_f32_e32 v170, 1.0, v170
	v_add_f32_e32 v171, 1.0, v171
	v_add_f32_e32 v172, 1.0, v172
	v_add_f32_e32 v173, 1.0, v173
	v_rcp_f32_e32 v170, v170
	v_rcp_f32_e32 v171, v171
	v_rcp_f32_e32 v172, v172
	v_rcp_f32_e32 v173, v173
	s_nop 0
	v_mul_f32_e32 v118, v118, v170
	v_mul_f32_e32 v119, v119, v171
	v_mul_f32_e32 v120, v120, v172
	v_mul_f32_e32 v121, v121, v173
	v_cvt_pk_bf16_f32 v164, v118, v119
	v_cvt_pk_bf16_f32 v165, v120, v121
	global_store_dwordx2 v148, v[164:165], s[8:9]
	s_add_u32 s8, s8, 0x7800
	s_addc_u32 s9, s9, 0
	s_waitcnt lgkmcnt(1)
	v_mul_f32_e32 v170, 0xbfb8aa3b, v122
	v_mul_f32_e32 v171, 0xbfb8aa3b, v123
	v_mul_f32_e32 v172, 0xbfb8aa3b, v124
	v_mul_f32_e32 v173, 0xbfb8aa3b, v125
	v_exp_f32_e32 v170, v170
	v_exp_f32_e32 v171, v171
	v_exp_f32_e32 v172, v172
	v_exp_f32_e32 v173, v173
	v_add_f32_e32 v170, 1.0, v170
	v_add_f32_e32 v171, 1.0, v171
	v_add_f32_e32 v172, 1.0, v172
	v_add_f32_e32 v173, 1.0, v173
	v_rcp_f32_e32 v170, v170
	v_rcp_f32_e32 v171, v171
	v_rcp_f32_e32 v172, v172
	v_rcp_f32_e32 v173, v173
	s_nop 0
	v_mul_f32_e32 v122, v122, v170
	v_mul_f32_e32 v123, v123, v171
	v_mul_f32_e32 v124, v124, v172
	v_mul_f32_e32 v125, v125, v173
	v_cvt_pk_bf16_f32 v166, v122, v123
	v_cvt_pk_bf16_f32 v167, v124, v125
	global_store_dwordx2 v148, v[166:167], s[8:9]
	s_add_u32 s8, s8, 0x7800
	s_addc_u32 s9, s9, 0
	s_waitcnt lgkmcnt(0)
	v_mul_f32_e32 v170, 0xbfb8aa3b, v126
	v_mul_f32_e32 v171, 0xbfb8aa3b, v127
	v_mul_f32_e32 v172, 0xbfb8aa3b, v128
	v_mul_f32_e32 v173, 0xbfb8aa3b, v129
	v_exp_f32_e32 v170, v170
	v_exp_f32_e32 v171, v171
	v_exp_f32_e32 v172, v172
	v_exp_f32_e32 v173, v173
	v_add_f32_e32 v170, 1.0, v170
	v_add_f32_e32 v171, 1.0, v171
	v_add_f32_e32 v172, 1.0, v172
	v_add_f32_e32 v173, 1.0, v173
	v_rcp_f32_e32 v170, v170
	v_rcp_f32_e32 v171, v171
	v_rcp_f32_e32 v172, v172
	v_rcp_f32_e32 v173, v173
	s_nop 0
	v_mul_f32_e32 v126, v126, v170
	v_mul_f32_e32 v127, v127, v171
	v_mul_f32_e32 v128, v128, v172
	v_mul_f32_e32 v129, v129, v173
	v_cvt_pk_bf16_f32 v168, v126, v127
	v_cvt_pk_bf16_f32 v169, v128, v129
	global_store_dwordx2 v148, v[168:169], s[8:9]
	s_add_u32 s8, s8, 0x7800
	s_addc_u32 s9, s9, 0
	ds_write2_b32 v146, v82, v66 offset0:0 offset1:32
	ds_write2_b32 v146, v83, v67 offset0:68 offset1:100
	ds_write2_b32 v146, v84, v68 offset0:136 offset1:168
	ds_write2_b32 v146, v85, v69 offset0:204 offset1:236
	v_add_u32_e32 v146, 0x880, v146
	ds_write2_b32 v146, v86, v70 offset0:0 offset1:32
	ds_write2_b32 v146, v87, v71 offset0:68 offset1:100
	ds_write2_b32 v146, v88, v72 offset0:136 offset1:168
	ds_write2_b32 v146, v89, v73 offset0:204 offset1:236
	v_add_u32_e32 v146, 0x880, v146
	ds_write2_b32 v146, v90, v74 offset0:0 offset1:32
	ds_write2_b32 v146, v91, v75 offset0:68 offset1:100
	ds_write2_b32 v146, v92, v76 offset0:136 offset1:168
	ds_write2_b32 v146, v93, v77 offset0:204 offset1:236
	v_add_u32_e32 v146, 0x880, v146
	ds_write2_b32 v146, v94, v78 offset0:0 offset1:32
	ds_write2_b32 v146, v95, v79 offset0:68 offset1:100
	ds_write2_b32 v146, v96, v80 offset0:136 offset1:168
	ds_write2_b32 v146, v97, v81 offset0:204 offset1:236
	v_subrev_u32_e32 v146, 0x1980, v146
	s_waitcnt lgkmcnt(0)
	ds_read_b128 v[66:69], v147
	ds_read_b128 v[70:73], v147 offset:1088
	ds_read_b128 v[74:77], v147 offset:2176
	ds_read_b128 v[78:81], v147 offset:3264
	ds_read_b128 v[82:85], v147 offset:4352
	ds_read_b128 v[86:89], v147 offset:5440
	ds_read_b128 v[90:93], v147 offset:6528
	ds_read_b128 v[94:97], v147 offset:7616
	s_waitcnt lgkmcnt(7)
	v_mul_f32_e32 v170, 0xbfb8aa3b, v66
	v_mul_f32_e32 v171, 0xbfb8aa3b, v67
	v_mul_f32_e32 v172, 0xbfb8aa3b, v68
	v_mul_f32_e32 v173, 0xbfb8aa3b, v69
	v_exp_f32_e32 v170, v170
	v_exp_f32_e32 v171, v171
	v_exp_f32_e32 v172, v172
	v_exp_f32_e32 v173, v173
	v_add_f32_e32 v170, 1.0, v170
	v_add_f32_e32 v171, 1.0, v171
	v_add_f32_e32 v172, 1.0, v172
	v_add_f32_e32 v173, 1.0, v173
	v_rcp_f32_e32 v170, v170
	v_rcp_f32_e32 v171, v171
	v_rcp_f32_e32 v172, v172
	v_rcp_f32_e32 v173, v173
	s_nop 0
	v_mul_f32_e32 v66, v66, v170
	v_mul_f32_e32 v67, v67, v171
	v_mul_f32_e32 v68, v68, v172
	v_mul_f32_e32 v69, v69, v173
	v_cvt_pk_bf16_f32 v154, v66, v67
	v_cvt_pk_bf16_f32 v155, v68, v69
	global_store_dwordx2 v148, v[154:155], s[8:9]
	s_add_u32 s8, s8, 0x7800
	s_addc_u32 s9, s9, 0
	s_waitcnt lgkmcnt(6)
	v_mul_f32_e32 v170, 0xbfb8aa3b, v70
	v_mul_f32_e32 v171, 0xbfb8aa3b, v71
	v_mul_f32_e32 v172, 0xbfb8aa3b, v72
	v_mul_f32_e32 v173, 0xbfb8aa3b, v73
	v_exp_f32_e32 v170, v170
	v_exp_f32_e32 v171, v171
	v_exp_f32_e32 v172, v172
	v_exp_f32_e32 v173, v173
	v_add_f32_e32 v170, 1.0, v170
	v_add_f32_e32 v171, 1.0, v171
	v_add_f32_e32 v172, 1.0, v172
	v_add_f32_e32 v173, 1.0, v173
	v_rcp_f32_e32 v170, v170
	v_rcp_f32_e32 v171, v171
	v_rcp_f32_e32 v172, v172
	v_rcp_f32_e32 v173, v173
	s_nop 0
	v_mul_f32_e32 v70, v70, v170
	v_mul_f32_e32 v71, v71, v171
	v_mul_f32_e32 v72, v72, v172
	v_mul_f32_e32 v73, v73, v173
	v_cvt_pk_bf16_f32 v156, v70, v71
	v_cvt_pk_bf16_f32 v157, v72, v73
	global_store_dwordx2 v148, v[156:157], s[8:9]
	s_add_u32 s8, s8, 0x7800
	s_addc_u32 s9, s9, 0
	s_waitcnt lgkmcnt(5)
	v_mul_f32_e32 v170, 0xbfb8aa3b, v74
	v_mul_f32_e32 v171, 0xbfb8aa3b, v75
	v_mul_f32_e32 v172, 0xbfb8aa3b, v76
	v_mul_f32_e32 v173, 0xbfb8aa3b, v77
	v_exp_f32_e32 v170, v170
	v_exp_f32_e32 v171, v171
	v_exp_f32_e32 v172, v172
	v_exp_f32_e32 v173, v173
	v_add_f32_e32 v170, 1.0, v170
	v_add_f32_e32 v171, 1.0, v171
	v_add_f32_e32 v172, 1.0, v172
	v_add_f32_e32 v173, 1.0, v173
	v_rcp_f32_e32 v170, v170
	v_rcp_f32_e32 v171, v171
	v_rcp_f32_e32 v172, v172
	v_rcp_f32_e32 v173, v173
	s_nop 0
	v_mul_f32_e32 v74, v74, v170
	v_mul_f32_e32 v75, v75, v171
	v_mul_f32_e32 v76, v76, v172
	v_mul_f32_e32 v77, v77, v173
	v_cvt_pk_bf16_f32 v158, v74, v75
	v_cvt_pk_bf16_f32 v159, v76, v77
	global_store_dwordx2 v148, v[158:159], s[8:9]
	s_add_u32 s8, s8, 0x7800
	s_addc_u32 s9, s9, 0
	s_waitcnt lgkmcnt(4)
	v_mul_f32_e32 v170, 0xbfb8aa3b, v78
	v_mul_f32_e32 v171, 0xbfb8aa3b, v79
	v_mul_f32_e32 v172, 0xbfb8aa3b, v80
	v_mul_f32_e32 v173, 0xbfb8aa3b, v81
	v_exp_f32_e32 v170, v170
	v_exp_f32_e32 v171, v171
	v_exp_f32_e32 v172, v172
	v_exp_f32_e32 v173, v173
	v_add_f32_e32 v170, 1.0, v170
	v_add_f32_e32 v171, 1.0, v171
	v_add_f32_e32 v172, 1.0, v172
	v_add_f32_e32 v173, 1.0, v173
	v_rcp_f32_e32 v170, v170
	v_rcp_f32_e32 v171, v171
	v_rcp_f32_e32 v172, v172
	v_rcp_f32_e32 v173, v173
	s_nop 0
	v_mul_f32_e32 v78, v78, v170
	v_mul_f32_e32 v79, v79, v171
	v_mul_f32_e32 v80, v80, v172
	v_mul_f32_e32 v81, v81, v173
	v_cvt_pk_bf16_f32 v160, v78, v79
	v_cvt_pk_bf16_f32 v161, v80, v81
	global_store_dwordx2 v148, v[160:161], s[8:9]
	s_add_u32 s8, s8, 0x7800
	s_addc_u32 s9, s9, 0
	s_waitcnt lgkmcnt(3)
	v_mul_f32_e32 v170, 0xbfb8aa3b, v82
	v_mul_f32_e32 v171, 0xbfb8aa3b, v83
	v_mul_f32_e32 v172, 0xbfb8aa3b, v84
	v_mul_f32_e32 v173, 0xbfb8aa3b, v85
	v_exp_f32_e32 v170, v170
	v_exp_f32_e32 v171, v171
	v_exp_f32_e32 v172, v172
	v_exp_f32_e32 v173, v173
	v_add_f32_e32 v170, 1.0, v170
	v_add_f32_e32 v171, 1.0, v171
	v_add_f32_e32 v172, 1.0, v172
	v_add_f32_e32 v173, 1.0, v173
	v_rcp_f32_e32 v170, v170
	v_rcp_f32_e32 v171, v171
	v_rcp_f32_e32 v172, v172
	v_rcp_f32_e32 v173, v173
	s_nop 0
	v_mul_f32_e32 v82, v82, v170
	v_mul_f32_e32 v83, v83, v171
	v_mul_f32_e32 v84, v84, v172
	v_mul_f32_e32 v85, v85, v173
	v_cvt_pk_bf16_f32 v162, v82, v83
	v_cvt_pk_bf16_f32 v163, v84, v85
	global_store_dwordx2 v148, v[162:163], s[8:9]
	s_add_u32 s8, s8, 0x7800
	s_addc_u32 s9, s9, 0
	s_waitcnt lgkmcnt(2)
	v_mul_f32_e32 v170, 0xbfb8aa3b, v86
	v_mul_f32_e32 v171, 0xbfb8aa3b, v87
	v_mul_f32_e32 v172, 0xbfb8aa3b, v88
	v_mul_f32_e32 v173, 0xbfb8aa3b, v89
	v_exp_f32_e32 v170, v170
	v_exp_f32_e32 v171, v171
	v_exp_f32_e32 v172, v172
	v_exp_f32_e32 v173, v173
	v_add_f32_e32 v170, 1.0, v170
	v_add_f32_e32 v171, 1.0, v171
	v_add_f32_e32 v172, 1.0, v172
	v_add_f32_e32 v173, 1.0, v173
	v_rcp_f32_e32 v170, v170
	v_rcp_f32_e32 v171, v171
	v_rcp_f32_e32 v172, v172
	v_rcp_f32_e32 v173, v173
	s_nop 0
	v_mul_f32_e32 v86, v86, v170
	v_mul_f32_e32 v87, v87, v171
	v_mul_f32_e32 v88, v88, v172
	v_mul_f32_e32 v89, v89, v173
	v_cvt_pk_bf16_f32 v164, v86, v87
	v_cvt_pk_bf16_f32 v165, v88, v89
	global_store_dwordx2 v148, v[164:165], s[8:9]
	s_add_u32 s8, s8, 0x7800
	s_addc_u32 s9, s9, 0
	s_waitcnt lgkmcnt(1)
	v_mul_f32_e32 v170, 0xbfb8aa3b, v90
	v_mul_f32_e32 v171, 0xbfb8aa3b, v91
	v_mul_f32_e32 v172, 0xbfb8aa3b, v92
	v_mul_f32_e32 v173, 0xbfb8aa3b, v93
	v_exp_f32_e32 v170, v170
	v_exp_f32_e32 v171, v171
	v_exp_f32_e32 v172, v172
	v_exp_f32_e32 v173, v173
	v_add_f32_e32 v170, 1.0, v170
	v_add_f32_e32 v171, 1.0, v171
	v_add_f32_e32 v172, 1.0, v172
	v_add_f32_e32 v173, 1.0, v173
	v_rcp_f32_e32 v170, v170
	v_rcp_f32_e32 v171, v171
	v_rcp_f32_e32 v172, v172
	v_rcp_f32_e32 v173, v173
	s_nop 0
	v_mul_f32_e32 v90, v90, v170
	v_mul_f32_e32 v91, v91, v171
	v_mul_f32_e32 v92, v92, v172
	v_mul_f32_e32 v93, v93, v173
	v_cvt_pk_bf16_f32 v166, v90, v91
	v_cvt_pk_bf16_f32 v167, v92, v93
	global_store_dwordx2 v148, v[166:167], s[8:9]
	s_add_u32 s8, s8, 0x7800
	s_addc_u32 s9, s9, 0
	s_waitcnt lgkmcnt(0)
	v_mul_f32_e32 v170, 0xbfb8aa3b, v94
	v_mul_f32_e32 v171, 0xbfb8aa3b, v95
	v_mul_f32_e32 v172, 0xbfb8aa3b, v96
	v_mul_f32_e32 v173, 0xbfb8aa3b, v97
	v_exp_f32_e32 v170, v170
	v_exp_f32_e32 v171, v171
	v_exp_f32_e32 v172, v172
	v_exp_f32_e32 v173, v173
	v_add_f32_e32 v170, 1.0, v170
	v_add_f32_e32 v171, 1.0, v171
	v_add_f32_e32 v172, 1.0, v172
	v_add_f32_e32 v173, 1.0, v173
	v_rcp_f32_e32 v170, v170
	v_rcp_f32_e32 v171, v171
	v_rcp_f32_e32 v172, v172
	v_rcp_f32_e32 v173, v173
	s_nop 0
	v_mul_f32_e32 v94, v94, v170
	v_mul_f32_e32 v95, v95, v171
	v_mul_f32_e32 v96, v96, v172
	v_mul_f32_e32 v97, v97, v173
	v_cvt_pk_bf16_f32 v168, v94, v95
	v_cvt_pk_bf16_f32 v169, v96, v97
	global_store_dwordx2 v148, v[168:169], s[8:9]
	s_add_u32 s8, s8, 0x7800
	s_addc_u32 s9, s9, 0
	ds_write2_b32 v146, v50, v34 offset0:0 offset1:32
	ds_write2_b32 v146, v51, v35 offset0:68 offset1:100
	ds_write2_b32 v146, v52, v36 offset0:136 offset1:168
	ds_write2_b32 v146, v53, v37 offset0:204 offset1:236
	v_add_u32_e32 v146, 0x880, v146
	ds_write2_b32 v146, v54, v38 offset0:0 offset1:32
	ds_write2_b32 v146, v55, v39 offset0:68 offset1:100
	ds_write2_b32 v146, v56, v40 offset0:136 offset1:168
	ds_write2_b32 v146, v57, v41 offset0:204 offset1:236
	v_add_u32_e32 v146, 0x880, v146
	ds_write2_b32 v146, v58, v42 offset0:0 offset1:32
	ds_write2_b32 v146, v59, v43 offset0:68 offset1:100
	ds_write2_b32 v146, v60, v44 offset0:136 offset1:168
	ds_write2_b32 v146, v61, v45 offset0:204 offset1:236
	v_add_u32_e32 v146, 0x880, v146
	ds_write2_b32 v146, v62, v46 offset0:0 offset1:32
	ds_write2_b32 v146, v63, v47 offset0:68 offset1:100
	ds_write2_b32 v146, v64, v48 offset0:136 offset1:168
	ds_write2_b32 v146, v65, v49 offset0:204 offset1:236
	v_subrev_u32_e32 v146, 0x1980, v146
	s_waitcnt lgkmcnt(0)
	ds_read_b128 v[34:37], v147
	ds_read_b128 v[38:41], v147 offset:1088
	ds_read_b128 v[42:45], v147 offset:2176
	ds_read_b128 v[46:49], v147 offset:3264
	ds_read_b128 v[50:53], v147 offset:4352
	ds_read_b128 v[54:57], v147 offset:5440
	ds_read_b128 v[58:61], v147 offset:6528
	ds_read_b128 v[62:65], v147 offset:7616
	s_waitcnt lgkmcnt(7)
	v_mul_f32_e32 v170, 0xbfb8aa3b, v34
	v_mul_f32_e32 v171, 0xbfb8aa3b, v35
	v_mul_f32_e32 v172, 0xbfb8aa3b, v36
	v_mul_f32_e32 v173, 0xbfb8aa3b, v37
	v_exp_f32_e32 v170, v170
	v_exp_f32_e32 v171, v171
	v_exp_f32_e32 v172, v172
	v_exp_f32_e32 v173, v173
	v_add_f32_e32 v170, 1.0, v170
	v_add_f32_e32 v171, 1.0, v171
	v_add_f32_e32 v172, 1.0, v172
	v_add_f32_e32 v173, 1.0, v173
	v_rcp_f32_e32 v170, v170
	v_rcp_f32_e32 v171, v171
	v_rcp_f32_e32 v172, v172
	v_rcp_f32_e32 v173, v173
	s_nop 0
	v_mul_f32_e32 v34, v34, v170
	v_mul_f32_e32 v35, v35, v171
	v_mul_f32_e32 v36, v36, v172
	v_mul_f32_e32 v37, v37, v173
	v_cvt_pk_bf16_f32 v154, v34, v35
	v_cvt_pk_bf16_f32 v155, v36, v37
	global_store_dwordx2 v148, v[154:155], s[8:9]
	s_add_u32 s8, s8, 0x7800
	s_addc_u32 s9, s9, 0
	s_waitcnt lgkmcnt(6)
	v_mul_f32_e32 v170, 0xbfb8aa3b, v38
	v_mul_f32_e32 v171, 0xbfb8aa3b, v39
	v_mul_f32_e32 v172, 0xbfb8aa3b, v40
	v_mul_f32_e32 v173, 0xbfb8aa3b, v41
	v_exp_f32_e32 v170, v170
	v_exp_f32_e32 v171, v171
	v_exp_f32_e32 v172, v172
	v_exp_f32_e32 v173, v173
	v_add_f32_e32 v170, 1.0, v170
	v_add_f32_e32 v171, 1.0, v171
	v_add_f32_e32 v172, 1.0, v172
	v_add_f32_e32 v173, 1.0, v173
	v_rcp_f32_e32 v170, v170
	v_rcp_f32_e32 v171, v171
	v_rcp_f32_e32 v172, v172
	v_rcp_f32_e32 v173, v173
	s_nop 0
	v_mul_f32_e32 v38, v38, v170
	v_mul_f32_e32 v39, v39, v171
	v_mul_f32_e32 v40, v40, v172
	v_mul_f32_e32 v41, v41, v173
	v_cvt_pk_bf16_f32 v156, v38, v39
	v_cvt_pk_bf16_f32 v157, v40, v41
	global_store_dwordx2 v148, v[156:157], s[8:9]
	s_add_u32 s8, s8, 0x7800
	s_addc_u32 s9, s9, 0
	s_waitcnt lgkmcnt(5)
	v_mul_f32_e32 v170, 0xbfb8aa3b, v42
	v_mul_f32_e32 v171, 0xbfb8aa3b, v43
	v_mul_f32_e32 v172, 0xbfb8aa3b, v44
	v_mul_f32_e32 v173, 0xbfb8aa3b, v45
	v_exp_f32_e32 v170, v170
	v_exp_f32_e32 v171, v171
	v_exp_f32_e32 v172, v172
	v_exp_f32_e32 v173, v173
	v_add_f32_e32 v170, 1.0, v170
	v_add_f32_e32 v171, 1.0, v171
	v_add_f32_e32 v172, 1.0, v172
	v_add_f32_e32 v173, 1.0, v173
	v_rcp_f32_e32 v170, v170
	v_rcp_f32_e32 v171, v171
	v_rcp_f32_e32 v172, v172
	v_rcp_f32_e32 v173, v173
	s_nop 0
	v_mul_f32_e32 v42, v42, v170
	v_mul_f32_e32 v43, v43, v171
	v_mul_f32_e32 v44, v44, v172
	v_mul_f32_e32 v45, v45, v173
	v_cvt_pk_bf16_f32 v158, v42, v43
	v_cvt_pk_bf16_f32 v159, v44, v45
	global_store_dwordx2 v148, v[158:159], s[8:9]
	s_add_u32 s8, s8, 0x7800
	s_addc_u32 s9, s9, 0
	s_waitcnt lgkmcnt(4)
	v_mul_f32_e32 v170, 0xbfb8aa3b, v46
	v_mul_f32_e32 v171, 0xbfb8aa3b, v47
	v_mul_f32_e32 v172, 0xbfb8aa3b, v48
	v_mul_f32_e32 v173, 0xbfb8aa3b, v49
	v_exp_f32_e32 v170, v170
	v_exp_f32_e32 v171, v171
	v_exp_f32_e32 v172, v172
	v_exp_f32_e32 v173, v173
	v_add_f32_e32 v170, 1.0, v170
	v_add_f32_e32 v171, 1.0, v171
	v_add_f32_e32 v172, 1.0, v172
	v_add_f32_e32 v173, 1.0, v173
	v_rcp_f32_e32 v170, v170
	v_rcp_f32_e32 v171, v171
	v_rcp_f32_e32 v172, v172
	v_rcp_f32_e32 v173, v173
	s_nop 0
	v_mul_f32_e32 v46, v46, v170
	v_mul_f32_e32 v47, v47, v171
	v_mul_f32_e32 v48, v48, v172
	v_mul_f32_e32 v49, v49, v173
	v_cvt_pk_bf16_f32 v160, v46, v47
	v_cvt_pk_bf16_f32 v161, v48, v49
	global_store_dwordx2 v148, v[160:161], s[8:9]
	s_add_u32 s8, s8, 0x7800
	s_addc_u32 s9, s9, 0
	s_waitcnt lgkmcnt(3)
	v_mul_f32_e32 v170, 0xbfb8aa3b, v50
	v_mul_f32_e32 v171, 0xbfb8aa3b, v51
	v_mul_f32_e32 v172, 0xbfb8aa3b, v52
	v_mul_f32_e32 v173, 0xbfb8aa3b, v53
	v_exp_f32_e32 v170, v170
	v_exp_f32_e32 v171, v171
	v_exp_f32_e32 v172, v172
	v_exp_f32_e32 v173, v173
	v_add_f32_e32 v170, 1.0, v170
	v_add_f32_e32 v171, 1.0, v171
	v_add_f32_e32 v172, 1.0, v172
	v_add_f32_e32 v173, 1.0, v173
	v_rcp_f32_e32 v170, v170
	v_rcp_f32_e32 v171, v171
	v_rcp_f32_e32 v172, v172
	v_rcp_f32_e32 v173, v173
	s_nop 0
	v_mul_f32_e32 v50, v50, v170
	v_mul_f32_e32 v51, v51, v171
	v_mul_f32_e32 v52, v52, v172
	v_mul_f32_e32 v53, v53, v173
	v_cvt_pk_bf16_f32 v162, v50, v51
	v_cvt_pk_bf16_f32 v163, v52, v53
	global_store_dwordx2 v148, v[162:163], s[8:9]
	s_add_u32 s8, s8, 0x7800
	s_addc_u32 s9, s9, 0
	s_waitcnt lgkmcnt(2)
	v_mul_f32_e32 v170, 0xbfb8aa3b, v54
	v_mul_f32_e32 v171, 0xbfb8aa3b, v55
	v_mul_f32_e32 v172, 0xbfb8aa3b, v56
	v_mul_f32_e32 v173, 0xbfb8aa3b, v57
	v_exp_f32_e32 v170, v170
	v_exp_f32_e32 v171, v171
	v_exp_f32_e32 v172, v172
	v_exp_f32_e32 v173, v173
	v_add_f32_e32 v170, 1.0, v170
	v_add_f32_e32 v171, 1.0, v171
	v_add_f32_e32 v172, 1.0, v172
	v_add_f32_e32 v173, 1.0, v173
	v_rcp_f32_e32 v170, v170
	v_rcp_f32_e32 v171, v171
	v_rcp_f32_e32 v172, v172
	v_rcp_f32_e32 v173, v173
	s_nop 0
	v_mul_f32_e32 v54, v54, v170
	v_mul_f32_e32 v55, v55, v171
	v_mul_f32_e32 v56, v56, v172
	v_mul_f32_e32 v57, v57, v173
	v_cvt_pk_bf16_f32 v164, v54, v55
	v_cvt_pk_bf16_f32 v165, v56, v57
	global_store_dwordx2 v148, v[164:165], s[8:9]
	s_add_u32 s8, s8, 0x7800
	s_addc_u32 s9, s9, 0
	s_waitcnt lgkmcnt(1)
	v_mul_f32_e32 v170, 0xbfb8aa3b, v58
	v_mul_f32_e32 v171, 0xbfb8aa3b, v59
	v_mul_f32_e32 v172, 0xbfb8aa3b, v60
	v_mul_f32_e32 v173, 0xbfb8aa3b, v61
	v_exp_f32_e32 v170, v170
	v_exp_f32_e32 v171, v171
	v_exp_f32_e32 v172, v172
	v_exp_f32_e32 v173, v173
	v_add_f32_e32 v170, 1.0, v170
	v_add_f32_e32 v171, 1.0, v171
	v_add_f32_e32 v172, 1.0, v172
	v_add_f32_e32 v173, 1.0, v173
	v_rcp_f32_e32 v170, v170
	v_rcp_f32_e32 v171, v171
	v_rcp_f32_e32 v172, v172
	v_rcp_f32_e32 v173, v173
	s_nop 0
	v_mul_f32_e32 v58, v58, v170
	v_mul_f32_e32 v59, v59, v171
	v_mul_f32_e32 v60, v60, v172
	v_mul_f32_e32 v61, v61, v173
	v_cvt_pk_bf16_f32 v166, v58, v59
	v_cvt_pk_bf16_f32 v167, v60, v61
	global_store_dwordx2 v148, v[166:167], s[8:9]
	s_add_u32 s8, s8, 0x7800
	s_addc_u32 s9, s9, 0
	s_waitcnt lgkmcnt(0)
	v_mul_f32_e32 v170, 0xbfb8aa3b, v62
	v_mul_f32_e32 v171, 0xbfb8aa3b, v63
	v_mul_f32_e32 v172, 0xbfb8aa3b, v64
	v_mul_f32_e32 v173, 0xbfb8aa3b, v65
	v_exp_f32_e32 v170, v170
	v_exp_f32_e32 v171, v171
	v_exp_f32_e32 v172, v172
	v_exp_f32_e32 v173, v173
	v_add_f32_e32 v170, 1.0, v170
	v_add_f32_e32 v171, 1.0, v171
	v_add_f32_e32 v172, 1.0, v172
	v_add_f32_e32 v173, 1.0, v173
	v_rcp_f32_e32 v170, v170
	v_rcp_f32_e32 v171, v171
	v_rcp_f32_e32 v172, v172
	v_rcp_f32_e32 v173, v173
	s_nop 0
	v_mul_f32_e32 v62, v62, v170
	v_mul_f32_e32 v63, v63, v171
	v_mul_f32_e32 v64, v64, v172
	v_mul_f32_e32 v65, v65, v173
	v_cvt_pk_bf16_f32 v168, v62, v63
	v_cvt_pk_bf16_f32 v169, v64, v65
	global_store_dwordx2 v148, v[168:169], s[8:9]
	s_add_u32 s8, s8, 0x7800
	s_addc_u32 s9, s9, 0
	ds_write2_b32 v146, v18, v2 offset0:0 offset1:32
	ds_write2_b32 v146, v19, v3 offset0:68 offset1:100
	ds_write2_b32 v146, v20, v4 offset0:136 offset1:168
	ds_write2_b32 v146, v21, v5 offset0:204 offset1:236
	v_add_u32_e32 v146, 0x880, v146
	ds_write2_b32 v146, v22, v6 offset0:0 offset1:32
	ds_write2_b32 v146, v23, v7 offset0:68 offset1:100
	ds_write2_b32 v146, v24, v8 offset0:136 offset1:168
	ds_write2_b32 v146, v25, v9 offset0:204 offset1:236
	v_add_u32_e32 v146, 0x880, v146
	ds_write2_b32 v146, v26, v10 offset0:0 offset1:32
	ds_write2_b32 v146, v27, v11 offset0:68 offset1:100
	ds_write2_b32 v146, v28, v12 offset0:136 offset1:168
	ds_write2_b32 v146, v29, v13 offset0:204 offset1:236
	v_add_u32_e32 v146, 0x880, v146
	ds_write2_b32 v146, v30, v14 offset0:0 offset1:32
	ds_write2_b32 v146, v31, v15 offset0:68 offset1:100
	ds_write2_b32 v146, v32, v16 offset0:136 offset1:168
	ds_write2_b32 v146, v33, v17 offset0:204 offset1:236
	v_subrev_u32_e32 v146, 0x1980, v146
	s_waitcnt lgkmcnt(0)
	ds_read_b128 v[2:5], v147
	ds_read_b128 v[6:9], v147 offset:1088
	ds_read_b128 v[10:13], v147 offset:2176
	ds_read_b128 v[14:17], v147 offset:3264
	ds_read_b128 v[18:21], v147 offset:4352
	ds_read_b128 v[22:25], v147 offset:5440
	ds_read_b128 v[26:29], v147 offset:6528
	ds_read_b128 v[30:33], v147 offset:7616
	s_waitcnt lgkmcnt(7)
	v_mul_f32_e32 v170, 0xbfb8aa3b, v2
	v_mul_f32_e32 v171, 0xbfb8aa3b, v3
	v_mul_f32_e32 v172, 0xbfb8aa3b, v4
	v_mul_f32_e32 v173, 0xbfb8aa3b, v5
	v_exp_f32_e32 v170, v170
	v_exp_f32_e32 v171, v171
	v_exp_f32_e32 v172, v172
	v_exp_f32_e32 v173, v173
	v_add_f32_e32 v170, 1.0, v170
	v_add_f32_e32 v171, 1.0, v171
	v_add_f32_e32 v172, 1.0, v172
	v_add_f32_e32 v173, 1.0, v173
	v_rcp_f32_e32 v170, v170
	v_rcp_f32_e32 v171, v171
	v_rcp_f32_e32 v172, v172
	v_rcp_f32_e32 v173, v173
	s_nop 0
	v_mul_f32_e32 v2, v2, v170
	v_mul_f32_e32 v3, v3, v171
	v_mul_f32_e32 v4, v4, v172
	v_mul_f32_e32 v5, v5, v173
	v_cvt_pk_bf16_f32 v154, v2, v3
	v_cvt_pk_bf16_f32 v155, v4, v5
	global_store_dwordx2 v148, v[154:155], s[8:9]
	s_add_u32 s8, s8, 0x7800
	s_addc_u32 s9, s9, 0
	s_waitcnt lgkmcnt(6)
	v_mul_f32_e32 v170, 0xbfb8aa3b, v6
	v_mul_f32_e32 v171, 0xbfb8aa3b, v7
	v_mul_f32_e32 v172, 0xbfb8aa3b, v8
	v_mul_f32_e32 v173, 0xbfb8aa3b, v9
	v_exp_f32_e32 v170, v170
	v_exp_f32_e32 v171, v171
	v_exp_f32_e32 v172, v172
	v_exp_f32_e32 v173, v173
	v_add_f32_e32 v170, 1.0, v170
	v_add_f32_e32 v171, 1.0, v171
	v_add_f32_e32 v172, 1.0, v172
	v_add_f32_e32 v173, 1.0, v173
	v_rcp_f32_e32 v170, v170
	v_rcp_f32_e32 v171, v171
	v_rcp_f32_e32 v172, v172
	v_rcp_f32_e32 v173, v173
	s_nop 0
	v_mul_f32_e32 v6, v6, v170
	v_mul_f32_e32 v7, v7, v171
	v_mul_f32_e32 v8, v8, v172
	v_mul_f32_e32 v9, v9, v173
	v_cvt_pk_bf16_f32 v156, v6, v7
	v_cvt_pk_bf16_f32 v157, v8, v9
	global_store_dwordx2 v148, v[156:157], s[8:9]
	s_add_u32 s8, s8, 0x7800
	s_addc_u32 s9, s9, 0
	s_waitcnt lgkmcnt(5)
	v_mul_f32_e32 v170, 0xbfb8aa3b, v10
	v_mul_f32_e32 v171, 0xbfb8aa3b, v11
	v_mul_f32_e32 v172, 0xbfb8aa3b, v12
	v_mul_f32_e32 v173, 0xbfb8aa3b, v13
	v_exp_f32_e32 v170, v170
	v_exp_f32_e32 v171, v171
	v_exp_f32_e32 v172, v172
	v_exp_f32_e32 v173, v173
	v_add_f32_e32 v170, 1.0, v170
	v_add_f32_e32 v171, 1.0, v171
	v_add_f32_e32 v172, 1.0, v172
	v_add_f32_e32 v173, 1.0, v173
	v_rcp_f32_e32 v170, v170
	v_rcp_f32_e32 v171, v171
	v_rcp_f32_e32 v172, v172
	v_rcp_f32_e32 v173, v173
	s_nop 0
	v_mul_f32_e32 v10, v10, v170
	v_mul_f32_e32 v11, v11, v171
	v_mul_f32_e32 v12, v12, v172
	v_mul_f32_e32 v13, v13, v173
	v_cvt_pk_bf16_f32 v158, v10, v11
	v_cvt_pk_bf16_f32 v159, v12, v13
	global_store_dwordx2 v148, v[158:159], s[8:9]
	s_add_u32 s8, s8, 0x7800
	s_addc_u32 s9, s9, 0
	s_waitcnt lgkmcnt(4)
	v_mul_f32_e32 v170, 0xbfb8aa3b, v14
	v_mul_f32_e32 v171, 0xbfb8aa3b, v15
	v_mul_f32_e32 v172, 0xbfb8aa3b, v16
	v_mul_f32_e32 v173, 0xbfb8aa3b, v17
	v_exp_f32_e32 v170, v170
	v_exp_f32_e32 v171, v171
	v_exp_f32_e32 v172, v172
	v_exp_f32_e32 v173, v173
	v_add_f32_e32 v170, 1.0, v170
	v_add_f32_e32 v171, 1.0, v171
	v_add_f32_e32 v172, 1.0, v172
	v_add_f32_e32 v173, 1.0, v173
	v_rcp_f32_e32 v170, v170
	v_rcp_f32_e32 v171, v171
	v_rcp_f32_e32 v172, v172
	v_rcp_f32_e32 v173, v173
	s_nop 0
	v_mul_f32_e32 v14, v14, v170
	v_mul_f32_e32 v15, v15, v171
	v_mul_f32_e32 v16, v16, v172
	v_mul_f32_e32 v17, v17, v173
	v_cvt_pk_bf16_f32 v160, v14, v15
	v_cvt_pk_bf16_f32 v161, v16, v17
	global_store_dwordx2 v148, v[160:161], s[8:9]
	s_add_u32 s8, s8, 0x7800
	s_addc_u32 s9, s9, 0
	s_waitcnt lgkmcnt(3)
	v_mul_f32_e32 v170, 0xbfb8aa3b, v18
	v_mul_f32_e32 v171, 0xbfb8aa3b, v19
	v_mul_f32_e32 v172, 0xbfb8aa3b, v20
	v_mul_f32_e32 v173, 0xbfb8aa3b, v21
	v_exp_f32_e32 v170, v170
	v_exp_f32_e32 v171, v171
	v_exp_f32_e32 v172, v172
	v_exp_f32_e32 v173, v173
	v_add_f32_e32 v170, 1.0, v170
	v_add_f32_e32 v171, 1.0, v171
	v_add_f32_e32 v172, 1.0, v172
	v_add_f32_e32 v173, 1.0, v173
	v_rcp_f32_e32 v170, v170
	v_rcp_f32_e32 v171, v171
	v_rcp_f32_e32 v172, v172
	v_rcp_f32_e32 v173, v173
	s_nop 0
	v_mul_f32_e32 v18, v18, v170
	v_mul_f32_e32 v19, v19, v171
	v_mul_f32_e32 v20, v20, v172
	v_mul_f32_e32 v21, v21, v173
	v_cvt_pk_bf16_f32 v162, v18, v19
	v_cvt_pk_bf16_f32 v163, v20, v21
	global_store_dwordx2 v148, v[162:163], s[8:9]
	s_add_u32 s8, s8, 0x7800
	s_addc_u32 s9, s9, 0
	s_waitcnt lgkmcnt(2)
	v_mul_f32_e32 v170, 0xbfb8aa3b, v22
	v_mul_f32_e32 v171, 0xbfb8aa3b, v23
	v_mul_f32_e32 v172, 0xbfb8aa3b, v24
	v_mul_f32_e32 v173, 0xbfb8aa3b, v25
	v_exp_f32_e32 v170, v170
	v_exp_f32_e32 v171, v171
	v_exp_f32_e32 v172, v172
	v_exp_f32_e32 v173, v173
	v_add_f32_e32 v170, 1.0, v170
	v_add_f32_e32 v171, 1.0, v171
	v_add_f32_e32 v172, 1.0, v172
	v_add_f32_e32 v173, 1.0, v173
	v_rcp_f32_e32 v170, v170
	v_rcp_f32_e32 v171, v171
	v_rcp_f32_e32 v172, v172
	v_rcp_f32_e32 v173, v173
	s_nop 0
	v_mul_f32_e32 v22, v22, v170
	v_mul_f32_e32 v23, v23, v171
	v_mul_f32_e32 v24, v24, v172
	v_mul_f32_e32 v25, v25, v173
	v_cvt_pk_bf16_f32 v164, v22, v23
	v_cvt_pk_bf16_f32 v165, v24, v25
	global_store_dwordx2 v148, v[164:165], s[8:9]
	s_add_u32 s8, s8, 0x7800
	s_addc_u32 s9, s9, 0
	s_waitcnt lgkmcnt(1)
	v_mul_f32_e32 v170, 0xbfb8aa3b, v26
	v_mul_f32_e32 v171, 0xbfb8aa3b, v27
	v_mul_f32_e32 v172, 0xbfb8aa3b, v28
	v_mul_f32_e32 v173, 0xbfb8aa3b, v29
	v_exp_f32_e32 v170, v170
	v_exp_f32_e32 v171, v171
	v_exp_f32_e32 v172, v172
	v_exp_f32_e32 v173, v173
	v_add_f32_e32 v170, 1.0, v170
	v_add_f32_e32 v171, 1.0, v171
	v_add_f32_e32 v172, 1.0, v172
	v_add_f32_e32 v173, 1.0, v173
	v_rcp_f32_e32 v170, v170
	v_rcp_f32_e32 v171, v171
	v_rcp_f32_e32 v172, v172
	v_rcp_f32_e32 v173, v173
	s_nop 0
	v_mul_f32_e32 v26, v26, v170
	v_mul_f32_e32 v27, v27, v171
	v_mul_f32_e32 v28, v28, v172
	v_mul_f32_e32 v29, v29, v173
	v_cvt_pk_bf16_f32 v166, v26, v27
	v_cvt_pk_bf16_f32 v167, v28, v29
	global_store_dwordx2 v148, v[166:167], s[8:9]
	s_add_u32 s8, s8, 0x7800
	s_addc_u32 s9, s9, 0
	s_waitcnt lgkmcnt(0)
	v_mul_f32_e32 v170, 0xbfb8aa3b, v30
	v_mul_f32_e32 v171, 0xbfb8aa3b, v31
	v_mul_f32_e32 v172, 0xbfb8aa3b, v32
	v_mul_f32_e32 v173, 0xbfb8aa3b, v33
	v_exp_f32_e32 v170, v170
	v_exp_f32_e32 v171, v171
	v_exp_f32_e32 v172, v172
	v_exp_f32_e32 v173, v173
	v_add_f32_e32 v170, 1.0, v170
	v_add_f32_e32 v171, 1.0, v171
	v_add_f32_e32 v172, 1.0, v172
	v_add_f32_e32 v173, 1.0, v173
	v_rcp_f32_e32 v170, v170
	v_rcp_f32_e32 v171, v171
	v_rcp_f32_e32 v172, v172
	v_rcp_f32_e32 v173, v173
	s_nop 0
	v_mul_f32_e32 v30, v30, v170
	v_mul_f32_e32 v31, v31, v171
	v_mul_f32_e32 v32, v32, v172
	v_mul_f32_e32 v33, v33, v173
	v_cvt_pk_bf16_f32 v168, v30, v31
	v_cvt_pk_bf16_f32 v169, v32, v33
	global_store_dwordx2 v148, v[168:169], s[8:9]
	s_add_u32 s8, s8, 0x7800
	s_addc_u32 s9, s9, 0
	s_add_i32 s70, s70, s10
	s_cmp_lt_i32 s70, s71
	s_waitcnt lgkmcnt(0)
	s_barrier
	s_cbranch_scc0 .LBB0_209
	s_branch .LBB0_215
.Lmy_g0e_std:
	s_cmp_lt_u32 s5, 3
	ds_write2_b32 v230, v114, v98 offset1:32
	ds_write2_b32 v230, v115, v99 offset0:65 offset1:97
	ds_write2_b32 v230, v116, v100 offset0:130 offset1:162
	ds_write2_b32 v230, v117, v101 offset0:195 offset1:227
	ds_write2_b32 v239, v118, v102 offset0:8 offset1:40
	ds_write2_b32 v239, v119, v103 offset0:73 offset1:105
	ds_write2_b32 v239, v120, v104 offset0:138 offset1:170
	ds_write2_b32 v239, v121, v105 offset0:203 offset1:235
	ds_write2_b32 v240, v122, v106 offset0:16 offset1:48
	ds_write2_b32 v240, v123, v107 offset0:81 offset1:113
	ds_write2_b32 v240, v124, v108 offset0:146 offset1:178
	ds_write2_b32 v240, v125, v109 offset0:211 offset1:243
	ds_write2_b32 v241, v126, v110 offset0:24 offset1:56
	ds_write2_b32 v241, v127, v111 offset0:89 offset1:121
	ds_write2_b32 v241, v128, v112 offset0:154 offset1:186
	ds_write2_b32 v241, v129, v113 offset0:219 offset1:251
	s_cselect_b64 s[8:9], -1, 0
	s_cmp_gt_u32 s4, 26
	s_waitcnt lgkmcnt(0)
	s_cselect_b64 s[34:35], -1, 0
	ds_read2_b32 v[154:155], v231 offset0:16 offset1:17
	ds_read2_b32 v[128:129], v231 offset0:18 offset1:19
	ds_read2_b32 v[126:127], v231 offset0:20 offset1:21
	ds_read2_b32 v[124:125], v231 offset0:22 offset1:23
	ds_read2_b32 v[122:123], v231 offset1:1
	ds_read2_b32 v[120:121], v231 offset0:4 offset1:5
	ds_read2_b32 v[114:115], v231 offset0:6 offset1:7
	ds_read2_b32 v[116:117], v231 offset0:2 offset1:3
	ds_read2_b32 v[162:163], v231 offset0:8 offset1:9
	ds_read2_b32 v[160:161], v231 offset0:10 offset1:11
	ds_read2_b32 v[158:159], v231 offset0:12 offset1:13
	ds_read2_b32 v[156:157], v231 offset0:14 offset1:15
	ds_read2_b32 v[152:153], v231 offset0:24 offset1:25
	ds_read2_b32 v[150:151], v231 offset0:26 offset1:27
	ds_read2_b32 v[148:149], v231 offset0:28 offset1:29
	ds_read2_b32 v[146:147], v231 offset0:30 offset1:31
	s_or_b64 s[8:9], s[34:35], s[8:9]
	s_cmp_gt_u32 s4, 21
	s_cselect_b64 vcc, -1, 0
	s_cmp_lt_u32 s4, 11
	v_cndmask_b32_e32 v144, 1.0, v213, vcc
	s_cselect_b64 vcc, -1, 0
	s_and_b64 s[34:35], vcc, exec
	s_cselect_b32 s7, s84, s86
	v_readlane_b32 s34, v242, 4
	s_cselect_b32 s5, s85, s87
	v_readlane_b32 s35, v242, 5
	s_add_u32 s34, s7, s34
	s_addc_u32 s35, s5, s35
	s_cmp_lt_i32 s4, 2
	v_mov_b32_e32 v141, v1
	s_cselect_b64 s[4:5], -1, 0
	v_lshl_add_u64 v[142:143], s[34:35], 0, v[140:141]
	s_and_b64 s[34:35], s[4:5], exec
	s_cselect_b32 s34, s28, s94
	v_readlane_b32 s36, v242, 12
	s_cselect_b32 s7, s29, s95
	v_readlane_b32 s37, v242, 13
	s_add_u32 s34, s34, s36
	s_addc_u32 s35, s7, s37
	s_movk_i32 s7, 0xf80
	v_and_or_b32 v0, v238, s7, v131
	s_waitcnt lgkmcnt(0)
	v_mul_u32_u24_e32 v0, 0x48, v0
	v_lshlrev_b32_e32 v0, 2, v0
	v_cndmask_b32_e32 v139, 1.0, v214, vcc
	v_lshl_add_u64 v[118:119], s[92:93], 0, v[0:1]
	s_mov_b64 s[96:97], -1
	s_and_b64 vcc, exec, s[30:31]
	s_cbranch_vccz .LBB0_239
	s_and_b64 vcc, exec, s[98:99]
	s_cbranch_vccz .LBB0_234
	s_and_b64 vcc, exec, s[2:3]
	s_cbranch_vccz .LBB0_227
	s_or_b64 s[68:69], s[82:83], s[8:9]
	s_andn2_b64 vcc, exec, s[68:69]
	s_waitcnt lgkmcnt(3)
	v_mov_b64_e32 v[110:111], v[152:153]
	s_waitcnt lgkmcnt(2)
	v_mov_b64_e32 v[112:113], v[150:151]
	s_waitcnt lgkmcnt(1)
	v_mov_b64_e32 v[172:173], v[148:149]
	s_waitcnt lgkmcnt(0)
	v_mov_b64_e32 v[174:175], v[146:147]
	v_mov_b64_e32 v[176:177], v[154:155]
	v_mov_b64_e32 v[178:179], v[128:129]
	v_mov_b64_e32 v[180:181], v[126:127]
	v_mov_b64_e32 v[190:191], v[124:125]
	v_mov_b64_e32 v[164:165], v[162:163]
	v_mov_b64_e32 v[166:167], v[160:161]
	v_mov_b64_e32 v[168:169], v[158:159]
	v_mov_b64_e32 v[170:171], v[156:157]
	v_mov_b64_e32 v[182:183], v[122:123]
	v_mov_b64_e32 v[188:189], v[116:117]
	v_mov_b64_e32 v[186:187], v[120:121]
	v_mov_b64_e32 v[184:185], v[114:115]
	s_cbranch_vccnz .LBB0_226
	v_mul_f32_e32 v0, 0xbfb8aa3b, v122
	v_exp_f32_e32 v0, v0
	v_mul_f32_e32 v98, 0xbfb8aa3b, v123
	v_exp_f32_e32 v98, v98
	v_mul_f32_e32 v100, 0xbfb8aa3b, v117
	v_add_f32_e32 v0, 1.0, v0
	v_exp_f32_e32 v100, v100
	v_add_f32_e32 v99, 1.0, v98
	v_rcp_f32_e32 v98, v0
	v_mul_f32_e32 v0, 0xbfb8aa3b, v116
	v_exp_f32_e32 v0, v0
	v_rcp_f32_e32 v99, v99
	v_add_f32_e32 v0, 1.0, v0
	v_pk_mul_f32 v[182:183], v[122:123], v[98:99]
	v_rcp_f32_e32 v98, v0
	v_add_f32_e32 v0, 1.0, v100
	v_rcp_f32_e32 v99, v0
	v_mul_f32_e32 v0, 0xbfb8aa3b, v120
	v_exp_f32_e32 v0, v0
	v_mul_f32_e32 v100, 0xbfb8aa3b, v121
	v_exp_f32_e32 v100, v100
	v_pk_mul_f32 v[188:189], v[116:117], v[98:99]
	v_add_f32_e32 v0, 1.0, v0
	v_rcp_f32_e32 v98, v0
	v_add_f32_e32 v0, 1.0, v100
	v_rcp_f32_e32 v99, v0
	v_mul_f32_e32 v0, 0xbfb8aa3b, v114
	v_exp_f32_e32 v0, v0
	v_mul_f32_e32 v100, 0xbfb8aa3b, v115
	v_exp_f32_e32 v100, v100
	v_pk_mul_f32 v[186:187], v[120:121], v[98:99]
	v_add_f32_e32 v0, 1.0, v0
	v_rcp_f32_e32 v98, v0
	v_add_f32_e32 v0, 1.0, v100
	v_rcp_f32_e32 v99, v0
	v_mul_f32_e32 v0, 0xbfb8aa3b, v162
	v_exp_f32_e32 v0, v0
	v_mul_f32_e32 v100, 0xbfb8aa3b, v163
	v_exp_f32_e32 v100, v100
	v_pk_mul_f32 v[184:185], v[114:115], v[98:99]
	v_add_f32_e32 v0, 1.0, v0
	v_rcp_f32_e32 v98, v0
	v_add_f32_e32 v0, 1.0, v100
	v_rcp_f32_e32 v99, v0
	v_mul_f32_e32 v0, 0xbfb8aa3b, v160
	v_exp_f32_e32 v0, v0
	v_mul_f32_e32 v100, 0xbfb8aa3b, v161
	v_exp_f32_e32 v100, v100
	v_pk_mul_f32 v[164:165], v[162:163], v[98:99]
	v_add_f32_e32 v0, 1.0, v0
	v_rcp_f32_e32 v98, v0
	v_add_f32_e32 v0, 1.0, v100
	v_rcp_f32_e32 v99, v0
	v_mul_f32_e32 v0, 0xbfb8aa3b, v158
	v_exp_f32_e32 v0, v0
	v_mul_f32_e32 v100, 0xbfb8aa3b, v159
	v_exp_f32_e32 v100, v100
	v_pk_mul_f32 v[166:167], v[160:161], v[98:99]
	v_add_f32_e32 v0, 1.0, v0
	v_rcp_f32_e32 v98, v0
	v_add_f32_e32 v0, 1.0, v100
	v_rcp_f32_e32 v99, v0
	v_mul_f32_e32 v0, 0xbfb8aa3b, v156
	v_exp_f32_e32 v0, v0
	v_mul_f32_e32 v100, 0xbfb8aa3b, v157
	v_exp_f32_e32 v100, v100
	v_pk_mul_f32 v[168:169], v[158:159], v[98:99]
	v_add_f32_e32 v0, 1.0, v0
	v_rcp_f32_e32 v98, v0
	v_add_f32_e32 v0, 1.0, v100
	v_rcp_f32_e32 v99, v0
	v_mul_f32_e32 v0, 0xbfb8aa3b, v154
	v_exp_f32_e32 v0, v0
	v_mul_f32_e32 v100, 0xbfb8aa3b, v155
	v_exp_f32_e32 v100, v100
	v_pk_mul_f32 v[170:171], v[156:157], v[98:99]
	v_add_f32_e32 v0, 1.0, v0
	v_rcp_f32_e32 v98, v0
	v_add_f32_e32 v0, 1.0, v100
	v_rcp_f32_e32 v99, v0
	v_mul_f32_e32 v0, 0xbfb8aa3b, v128
	v_exp_f32_e32 v0, v0
	v_mul_f32_e32 v100, 0xbfb8aa3b, v129
	v_exp_f32_e32 v100, v100
	v_pk_mul_f32 v[176:177], v[154:155], v[98:99]
	v_add_f32_e32 v0, 1.0, v0
	v_rcp_f32_e32 v98, v0
	v_add_f32_e32 v0, 1.0, v100
	v_rcp_f32_e32 v99, v0
	v_mul_f32_e32 v0, 0xbfb8aa3b, v126
	v_exp_f32_e32 v0, v0
	v_mul_f32_e32 v100, 0xbfb8aa3b, v127
	v_exp_f32_e32 v100, v100
	v_pk_mul_f32 v[178:179], v[128:129], v[98:99]
	v_add_f32_e32 v0, 1.0, v0
	v_rcp_f32_e32 v98, v0
	v_add_f32_e32 v0, 1.0, v100
	v_rcp_f32_e32 v99, v0
	v_mul_f32_e32 v0, 0xbfb8aa3b, v124
	v_exp_f32_e32 v0, v0
	v_mul_f32_e32 v100, 0xbfb8aa3b, v125
	v_exp_f32_e32 v100, v100
	v_pk_mul_f32 v[180:181], v[126:127], v[98:99]
	v_add_f32_e32 v0, 1.0, v0
	v_rcp_f32_e32 v98, v0
	v_add_f32_e32 v0, 1.0, v100
	v_rcp_f32_e32 v99, v0
	v_mul_f32_e32 v0, 0xbfb8aa3b, v152
	v_exp_f32_e32 v0, v0
	v_mul_f32_e32 v100, 0xbfb8aa3b, v153
	v_exp_f32_e32 v100, v100
	v_pk_mul_f32 v[190:191], v[124:125], v[98:99]
	v_add_f32_e32 v0, 1.0, v0
	v_mul_f32_e32 v99, 0xbfb8aa3b, v150
	v_rcp_f32_e32 v98, v0
	v_add_f32_e32 v0, 1.0, v100
	v_exp_f32_e32 v100, v99
	v_mul_f32_e32 v99, 0xbfb8aa3b, v151
	v_exp_f32_e32 v101, v99
	v_rcp_f32_e32 v99, v0
	v_add_f32_e32 v0, 1.0, v100
	v_rcp_f32_e32 v100, v0
	v_add_f32_e32 v0, 1.0, v101
	v_mul_f32_e32 v101, 0xbfb8aa3b, v148
	v_exp_f32_e32 v102, v101
	v_mul_f32_e32 v101, 0xbfb8aa3b, v149
	v_exp_f32_e32 v103, v101
	v_rcp_f32_e32 v101, v0
	v_add_f32_e32 v0, 1.0, v102
	v_rcp_f32_e32 v102, v0
	v_add_f32_e32 v0, 1.0, v103
	v_mul_f32_e32 v103, 0xbfb8aa3b, v146
	v_exp_f32_e32 v104, v103
	v_mul_f32_e32 v103, 0xbfb8aa3b, v147
	v_exp_f32_e32 v105, v103
	v_rcp_f32_e32 v103, v0
	v_add_f32_e32 v0, 1.0, v104
	v_rcp_f32_e32 v104, v0
	v_add_f32_e32 v0, 1.0, v105
	v_rcp_f32_e32 v105, v0
	v_pk_mul_f32 v[110:111], v[152:153], v[98:99]
	v_pk_mul_f32 v[112:113], v[150:151], v[100:101]
	v_pk_mul_f32 v[172:173], v[148:149], v[102:103]
	v_pk_mul_f32 v[174:175], v[146:147], v[104:105]
